# stack: attention prefetch+V b128 layout, permlane max-reduction, HGRN prefetch un-stalled + batched POST LDS reads, RWKV prep loads direct-to-home
# speedup vs baseline: 1.0211x; 1.0018x over previous
; #define HG_LD(X, tl_) do { const float* f_ = sF + (tl_) * 128 + seg * 4; const float* q_ = sQ + (tl_) * 128 + seg * 4;   \
;                 X##f0 = *(const f32x4*)(f_); X##f1 = *(const f32x4*)(f_ + 64); X##q0 = *(const f32x4*)(q_); X##q1 = *(const f32x4*)(q_ + 64); \
;                 X##va = sDV[(tl_) * 64 + cp]; X##vb = sDV[(tl_) * 64 + 32 + cp]; } while (0)
; __device__ __forceinline__ void phase_hgrn(KP P, int l_, unsigned char* shm) {
;     ...
;             if (c + 1 < SEQ / T) HG_LOAD((c + 1) * T);
;     ...
;             {
;                 f32x4 Af0, Af1, Aq0, Aq1; float Ava, Avb;
;                 f32x4 Bf0, Bf1, Bq0, Bq1; float Bva, Bvb;
;                 HG_LD(A, 0);
.LBB0_2158:
	s_add_i32 s25, s26, 1
	s_cmp_lg_u32 s26, 63
	s_cselect_b64 s[20:21], -1, 0
	s_cmp_eq_u32 s26, 63
	s_cbranch_scc1 .LBB0_2162
	s_lshl_b32 s52, s25, 5
	v_lshl_add_u64 v[0:1], v[54:55], 0, s[52:53]
	v_lshlrev_b64 v[0:1], 12, v[0:1]
	v_lshl_add_u64 v[18:19], v[56:57], 0, v[0:1]
	v_add_co_u32_e32 v12, vcc, s66, v18
	s_mov_b32 s17, s53
	s_nop 0
	v_addc_co_u32_e32 v13, vcc, 0, v19, vcc
	v_add_co_u32_e32 v20, vcc, s67, v18
	v_lshl_add_u64 v[14:15], v[18:19], 0, s[90:91]
	s_nop 0
	v_addc_co_u32_e32 v21, vcc, 0, v19, vcc
	v_lshl_add_u64 v[0:1], v[18:19], 0, s[16:17]
	v_lshl_add_u64 v[14:15], v[14:15], 0, s[16:17]
	v_lshl_add_u64 v[22:23], v[18:19], 0, s[92:93]
	v_add_co_u32_e32 v24, vcc, 0x3000, v18
	global_load_ushort v213, v[18:19], off
	global_load_ushort v214, v[18:19], off offset:128
	global_load_ushort v215, v[18:19], off offset:1024
	global_load_ushort v216, v[18:19], off offset:1152
	v_addc_co_u32_e32 v25, vcc, 0, v19, vcc
	global_load_ushort v217, v[0:1], off offset:2048
	s_nop 0
	global_load_ushort v218, v[20:21], off offset:-4096
	global_load_ushort v219, v[12:13], off offset:128
	global_load_ushort v220, v[12:13], off offset:1024
	s_nop 0
	global_load_ushort v221, v[12:13], off offset:1152
	s_movk_i32 s0, 0x7fc
	global_load_ushort v222, v[14:15], off offset:2048
	global_load_ushort v223, v[20:21], off
	s_nop 0
	global_load_ushort v224, v[20:21], off offset:128
	global_load_ushort v225, v[20:21], off offset:1024
	global_load_ushort v226, v[20:21], off offset:1152
	v_lshl_add_u64 v[20:21], v[22:23], 0, s[16:17]
	global_load_ushort v227, v[20:21], off offset:2048
	v_lshl_add_u64 v[22:23], v[18:19], 0, s[94:95]
	global_load_ushort v242, v[24:25], off
	global_load_ushort v243, v[24:25], off offset:128
	global_load_ushort v244, v[24:25], off offset:1024
	global_load_ushort v245, v[24:25], off offset:1152
	v_lshl_add_u64 v[22:23], v[22:23], 0, s[16:17]
	global_load_ushort v246, v[22:23], off offset:2048
	v_add_u32_e32 v23, s52, v40
	v_cmp_gt_i32_e32 vcc, s0, v23
	v_mov_b32_e32 v247, 0
	s_and_saveexec_b64 s[22:23], vcc
	s_cbranch_execz .LBB0_2161
	v_add_u32_e32 v24, 4, v23
	v_ashrrev_i32_e32 v25, 31, v24
	v_lshl_add_u64 v[24:25], s[18:19], 0, v[24:25]
	v_lshlrev_b64 v[24:25], 12, v[24:25]
	v_lshl_add_u64 v[24:25], v[60:61], 0, v[24:25]
	global_load_ushort v247, v[24:25], off offset:2048
.LBB0_2161:
	s_or_b64 exec, exec, s[22:23]
.LBB0_2162:
	ds_read_b128 v[18:21], v111
	ds_read_b128 v[14:17], v111 offset:256
	ds_read_b128 v[10:13], v111 offset:16384
	ds_read_b128 v[6:9], v111 offset:16640
	ds_read2_b32 v[78:79], v116 offset1:32
	s_mov_b32 s17, -2
	v_mov_b32_e32 v129, v110
	v_mov_b32_e32 v130, v109
	v_mov_b32_e32 v131, v108
	v_mov_b32_e32 v132, v107
	s_waitcnt lgkmcnt(0)
	v_mov_b32_e32 v4, v79
	s_branch .LBB0_2164

; #define HG_LD(X, tl_) do { const float* f_ = sF + (tl_) * 128 + seg * 4; const float* q_ = sQ + (tl_) * 128 + seg * 4;   \
;                 X##f0 = *(const f32x4*)(f_); X##f1 = *(const f32x4*)(f_ + 64); X##q0 = *(const f32x4*)(q_); X##q1 = *(const f32x4*)(q_ + 64); \
;                 X##va = sDV[(tl_) * 64 + cp]; X##vb = sDV[(tl_) * 64 + 32 + cp]; } while (0)
; __device__ __forceinline__ void phase_hgrn(KP P, int l_, unsigned char* shm) {
;     ...
;             {
;                 f32x4 Af0, Af1, Aq0, Aq1; float Ava, Avb;
;                 f32x4 Bf0, Bf1, Bq0, Bq1; float Bva, Bvb;
;                 HG_LD(A, 0);
; #pragma unroll 2
;                 for (int tl = 0; tl < T; tl += 2) {
;                     HG_LD(B, tl + 1);
;                     HG_STEP(A, tl);
;                     HG_LD(A, tl + 2);
;                     HG_STEP(B, tl + 1);
;                 }
.LBB0_2166:
	s_or_b64 exec, exec, s[22:23]
	s_waitcnt lgkmcnt(2)
	v_mov_b32_e32 v4, v81
	ds_read_b128 v[18:21], v129 offset:512
	ds_read_b128 v[14:17], v129 offset:768
	ds_read_b128 v[10:13], v129 offset:16896
	ds_read_b128 v[6:9], v129 offset:17152
	ds_read2_b32 v[62:63], v130 offset0:64 offset1:96
	v_pk_fma_f32 v[70:71], v[70:71], v[36:37], v[80:81] op_sel_hi:[1,1,0]
	v_pk_fma_f32 v[76:77], v[36:37], v[76:77], v[4:5] op_sel_hi:[1,1,0]
	v_pk_fma_f32 v[64:65], v[64:65], v[34:35], v[80:81] op_sel_hi:[1,1,0]
	v_pk_fma_f32 v[78:79], v[34:35], v[82:83], v[4:5] op_sel_hi:[1,1,0]
	v_pk_fma_f32 v[82:83], v[68:69], v[30:31], v[80:81] op_sel_hi:[1,1,0]
	v_pk_fma_f32 v[84:85], v[74:75], v[30:31], v[4:5] op_sel_hi:[1,1,0]
	v_pk_fma_f32 v[86:87], v[66:67], v[32:33], v[80:81] op_sel_hi:[1,1,0]
	v_pk_fma_f32 v[88:89], v[72:73], v[32:33], v[4:5] op_sel_hi:[1,1,0]
	v_pk_mul_f32 v[30:31], v[28:29], v[70:71]
	v_pk_mul_f32 v[28:29], v[28:29], v[76:77]
	v_pk_fma_f32 v[30:31], v[26:27], v[64:65], v[30:31]
	v_pk_fma_f32 v[26:27], v[26:27], v[78:79], v[28:29]
	v_pk_mul_f32 v[28:29], v[24:25], v[86:87]
	v_pk_mul_f32 v[24:25], v[24:25], v[88:89]
	v_pk_fma_f32 v[28:29], v[22:23], v[82:83], v[28:29]
	v_pk_fma_f32 v[22:23], v[22:23], v[84:85], v[24:25]
	v_pk_add_f32 v[28:29], v[30:31], v[28:29]
	v_pk_add_f32 v[22:23], v[26:27], v[22:23]
	v_add_f32_e32 v4, v28, v29
	v_add_f32_e32 v22, v22, v23
	s_nop 0
	v_add_f32_dpp v4, v4, v4 quad_perm:[1,0,3,2] row_mask:0xf bank_mask:0xf bound_ctrl:1
	v_add_f32_dpp v22, v22, v22 quad_perm:[1,0,3,2] row_mask:0xf bank_mask:0xf bound_ctrl:1
	s_nop 0
	v_mov_b32_dpp v23, v4 quad_perm:[2,3,0,1] row_mask:0xf bank_mask:0xf bound_ctrl:1
	v_mov_b32_dpp v24, v22 quad_perm:[2,3,0,1] row_mask:0xf bank_mask:0xf bound_ctrl:1
	s_and_saveexec_b64 s[22:23], s[8:9]
	s_cbranch_execz .LBB0_2168
	v_add_f32_e32 v4, v4, v23
	v_add_f32_e32 v22, v22, v24
	ds_write_b32 v132, v4 offset:1024
	ds_write_b32 v131, v22 offset:1024
.LBB0_2168:
	s_or_b64 exec, exec, s[22:23]
	s_waitcnt lgkmcnt(2)
	v_mov_b32_e32 v4, v63
	ds_read_b128 v[34:37], v129 offset:1024
	ds_read_b128 v[30:33], v129 offset:1280
	ds_read_b128 v[26:29], v129 offset:17408
	ds_read_b128 v[22:25], v129 offset:17664
	ds_read2_b32 v[66:67], v130 offset0:128 offset1:160
	v_pk_fma_f32 v[70:71], v[20:21], v[70:71], v[62:63] op_sel_hi:[1,1,0]
	v_pk_fma_f32 v[72:73], v[20:21], v[76:77], v[4:5] op_sel_hi:[1,1,0]
	v_pk_fma_f32 v[64:65], v[18:19], v[64:65], v[62:63] op_sel_hi:[1,1,0]
	v_pk_fma_f32 v[68:69], v[18:19], v[78:79], v[4:5] op_sel_hi:[1,1,0]
	v_pk_fma_f32 v[74:75], v[14:15], v[82:83], v[62:63] op_sel_hi:[1,1,0]
	v_pk_fma_f32 v[80:81], v[14:15], v[84:85], v[4:5] op_sel_hi:[1,1,0]
	v_pk_fma_f32 v[82:83], v[16:17], v[86:87], v[62:63] op_sel_hi:[1,1,0]
	v_pk_fma_f32 v[84:85], v[16:17], v[88:89], v[4:5] op_sel_hi:[1,1,0]
	v_pk_mul_f32 v[14:15], v[12:13], v[70:71]
	v_pk_mul_f32 v[12:13], v[12:13], v[72:73]
	v_pk_fma_f32 v[14:15], v[10:11], v[64:65], v[14:15]
	v_pk_fma_f32 v[10:11], v[10:11], v[68:69], v[12:13]
	v_pk_mul_f32 v[12:13], v[8:9], v[82:83]
	v_pk_mul_f32 v[8:9], v[8:9], v[84:85]
	v_pk_fma_f32 v[12:13], v[6:7], v[74:75], v[12:13]
	v_pk_fma_f32 v[6:7], v[6:7], v[80:81], v[8:9]
	v_pk_add_f32 v[12:13], v[12:13], v[14:15]
	v_pk_add_f32 v[6:7], v[6:7], v[10:11]
	v_add_f32_e32 v4, v12, v13
	v_add_f32_e32 v6, v6, v7
	s_nop 0
	v_add_f32_dpp v4, v4, v4 quad_perm:[1,0,3,2] row_mask:0xf bank_mask:0xf bound_ctrl:1
	v_add_f32_dpp v6, v6, v6 quad_perm:[1,0,3,2] row_mask:0xf bank_mask:0xf bound_ctrl:1
	s_nop 0
	v_mov_b32_dpp v7, v4 quad_perm:[2,3,0,1] row_mask:0xf bank_mask:0xf bound_ctrl:1
	v_mov_b32_dpp v8, v6 quad_perm:[2,3,0,1] row_mask:0xf bank_mask:0xf bound_ctrl:1
	s_and_saveexec_b64 s[22:23], s[8:9]
	s_cbranch_execz .LBB0_2170
	v_add_f32_e32 v4, v4, v7
	v_add_f32_e32 v6, v6, v8
	ds_write_b32 v132, v4 offset:2048
	ds_write_b32 v131, v6 offset:2048
.LBB0_2170:
	s_or_b64 exec, exec, s[22:23]
	s_waitcnt lgkmcnt(2)
	v_mov_b32_e32 v86, v67
	v_pk_fma_f32 v[70:71], v[70:71], v[36:37], v[66:67] op_sel_hi:[1,1,0]
	v_pk_fma_f32 v[76:77], v[36:37], v[72:73], v[86:87] op_sel_hi:[1,1,0]
	v_pk_fma_f32 v[64:65], v[64:65], v[34:35], v[66:67] op_sel_hi:[1,1,0]
	v_pk_fma_f32 v[62:63], v[34:35], v[68:69], v[86:87] op_sel_hi:[1,1,0]
	v_pk_fma_f32 v[68:69], v[74:75], v[30:31], v[66:67] op_sel_hi:[1,1,0]
	v_pk_fma_f32 v[74:75], v[80:81], v[30:31], v[86:87] op_sel_hi:[1,1,0]
	v_pk_fma_f32 v[66:67], v[82:83], v[32:33], v[66:67] op_sel_hi:[1,1,0]
	v_pk_fma_f32 v[72:73], v[84:85], v[32:33], v[86:87] op_sel_hi:[1,1,0]
	v_pk_mul_f32 v[30:31], v[28:29], v[70:71]
	v_pk_mul_f32 v[28:29], v[28:29], v[76:77]
	v_pk_fma_f32 v[30:31], v[26:27], v[64:65], v[30:31]
	v_pk_fma_f32 v[26:27], v[26:27], v[62:63], v[28:29]
	v_pk_mul_f32 v[28:29], v[24:25], v[66:67]
	v_pk_mul_f32 v[24:25], v[24:25], v[72:73]
	v_pk_fma_f32 v[28:29], v[22:23], v[68:69], v[28:29]
	v_pk_fma_f32 v[22:23], v[22:23], v[74:75], v[24:25]
	v_pk_add_f32 v[28:29], v[30:31], v[28:29]
	v_pk_add_f32 v[22:23], v[26:27], v[22:23]
	v_add_f32_e32 v24, v28, v29
	v_add_f32_e32 v23, v22, v23
	ds_read2_b32 v[78:79], v130 offset0:192 offset1:224
	ds_read_b128 v[18:21], v129 offset:1536
	ds_read_b128 v[14:17], v129 offset:1792
	ds_read_b128 v[10:13], v129 offset:17920
	ds_read_b128 v[6:9], v129 offset:18176
	v_add_f32_dpp v22, v24, v24 quad_perm:[1,0,3,2] row_mask:0xf bank_mask:0xf bound_ctrl:1
	v_add_f32_dpp v23, v23, v23 quad_perm:[1,0,3,2] row_mask:0xf bank_mask:0xf bound_ctrl:1
	s_waitcnt lgkmcnt(4)
	v_mov_b32_e32 v4, v79
	v_mov_b32_dpp v24, v22 quad_perm:[2,3,0,1] row_mask:0xf bank_mask:0xf bound_ctrl:1
	v_mov_b32_dpp v25, v23 quad_perm:[2,3,0,1] row_mask:0xf bank_mask:0xf bound_ctrl:1
	s_and_saveexec_b64 s[22:23], s[8:9]
	s_cbranch_execz .LBB0_2163
	v_add_f32_e32 v22, v22, v24
	v_add_f32_e32 v23, v23, v25
	ds_write_b32 v132, v22 offset:3072
	ds_write_b32 v131, v23 offset:3072
	s_branch .LBB0_2163
; __device__ __forceinline__ u16 f2bf(float f) { return (u16)(cvt_pk_bf16(f, 0.f) & 0xffffu); }
; __device__ __forceinline__ void phase_hgrn(KP P, int l_, unsigned char* shm) {
;     ...
;             __syncthreads();
; #pragma unroll
;             for (int i = 0; i < 4; ++i) { const int tl = wave * 4 + i; const size_t tok = (size_t)b * SEQ + c * T + tl;
;                 const f32x4 oa = *(const f32x4*)(sO + tl * 256 + lane * 4);
;                 const float o = ((oa[0] + oa[1]) + (oa[2] + oa[3])) + sVN[tl * 64 + lane] * sQS[tl];
;                 OC[tok * 512 + h * 128 + half * 64 + lane] = f2bf(o); }
;             if (c + 1 < SEQ / T) HG_PREP();
.LBB0_2172:
	s_waitcnt lgkmcnt(0)
	s_barrier
	s_waitcnt vmcnt(0)
	v_perm_b32 v1, v246, v227, s82
	v_perm_b32 v0, v222, v217, s82
	v_perm_b32 v124, v221, v216, s82
	v_perm_b32 v128, v245, v226, s82
	v_perm_b32 v123, v220, v215, s82
	v_perm_b32 v127, v244, v225, s82
	v_perm_b32 v122, v219, v214, s82
	v_perm_b32 v126, v243, v224, s82
	v_perm_b32 v121, v218, v213, s82
	v_perm_b32 v125, v242, v223, s82
	v_mov_b32_e32 v2, v247
	ds_read_b128 v[158:161], v112 offset:49152
	ds_read_b128 v[162:165], v113 offset:49152
	ds_read_b128 v[166:169], v114 offset:49152
	ds_read_b128 v[170:173], v115 offset:49152
	v_add_u32_e32 v6, v90, v92
	v_add_u32_e32 v7, v90, v96
	v_add_u32_e32 v8, v90, v100
	v_add_u32_e32 v9, v90, v104
	ds_read_b32 v174, v6 offset:40960
	ds_read_b32 v175, v94
	ds_read_b32 v176, v7 offset:40960
	ds_read_b32 v186, v98
	ds_read_b32 v187, v8 offset:40960
	ds_read_b32 v235, v102
	ds_read_b32 v239, v9 offset:40960
	ds_read_b32 v240, v106
	s_lshl_b32 s0, s26, 5
	s_add_u32 s22, s18, s0
	s_addc_u32 s23, s19, 0
	s_and_b64 vcc, exec, s[20:21]
	v_lshl_add_u64 v[10:11], s[22:23], 0, v[40:41]
	s_waitcnt lgkmcnt(0)
	v_add_f32_e32 v4, v158, v159
	v_add_f32_e32 v6, v160, v161
	v_add_f32_e32 v4, v4, v6
	v_fmac_f32_e32 v4, v174, v175
	v_lshlrev_b64 v[6:7], 10, v[10:11]
	v_lshl_add_u64 v[6:7], v[58:59], 0, v[6:7]
	s_nop 0
	v_cvt_pk_bf16_f32 v4, v4, v5
	global_store_short v[6:7], v4, off
	v_lshl_add_u64 v[10:11], s[22:23], 0, v[48:49]
	v_add_f32_e32 v8, v162, v163
	v_add_f32_e32 v9, v164, v165
	v_add_f32_e32 v8, v8, v9
	v_fmac_f32_e32 v8, v176, v186
	v_lshlrev_b64 v[6:7], 10, v[10:11]
	v_lshl_add_u64 v[6:7], v[58:59], 0, v[6:7]
	s_nop 0
	v_cvt_pk_bf16_f32 v8, v8, v5
	global_store_short v[6:7], v8, off
	v_lshl_add_u64 v[10:11], s[22:23], 0, v[50:51]
	v_add_f32_e32 v4, v166, v167
	v_add_f32_e32 v9, v168, v169
	v_add_f32_e32 v4, v4, v9
	v_fmac_f32_e32 v4, v187, v235
	v_lshlrev_b64 v[6:7], 10, v[10:11]
	v_lshl_add_u64 v[6:7], v[58:59], 0, v[6:7]
	s_nop 0
	v_cvt_pk_bf16_f32 v4, v4, v5
	global_store_short v[6:7], v4, off
	v_lshl_add_u64 v[10:11], s[22:23], 0, v[52:53]
	v_add_f32_e32 v8, v170, v171
	v_add_f32_e32 v9, v172, v173
	v_add_f32_e32 v8, v8, v9
	v_fmac_f32_e32 v8, v239, v240
	v_lshlrev_b64 v[6:7], 10, v[10:11]
	v_lshl_add_u64 v[6:7], v[58:59], 0, v[6:7]
	s_nop 0
	v_cvt_pk_bf16_f32 v8, v8, v5
	global_store_short v[6:7], v8, off
	s_cbranch_vccz .LBB0_2157
	v_lshlrev_b32_e32 v4, 16, v121
	v_mul_f32_e32 v6, 0xbfb8aa3b, v4
	v_exp_f32_e32 v6, v6
	v_lshlrev_b32_e32 v7, 16, v122
	v_mul_f32_e32 v8, 0xbfb8aa3b, v7
	v_exp_f32_e32 v8, v8
	v_add_f32_e32 v6, 1.0, v6
	v_rcp_f32_e32 v6, v6
	v_lshlrev_b32_e32 v9, 16, v123
	v_add_f32_e32 v8, 1.0, v8
	v_mul_f32_e32 v9, 0xbfb8aa3b, v9
	v_rcp_f32_e32 v8, v8
	v_mul_f32_e32 v6, v6, v4
	v_exp_f32_e32 v4, v9
	v_lshlrev_b32_e32 v9, 16, v124
	v_mul_f32_e32 v9, 0xbfb8aa3b, v9
	v_exp_f32_e32 v9, v9
	v_mul_f32_e32 v10, v8, v7
	ds_write2st64_b32 v91, v6, v10 offset0:64 offset1:65
	v_fmac_f32_e32 v6, v8, v7
	v_add_f32_e32 v4, 1.0, v4
	v_add_f32_e32 v9, 1.0, v9
	v_add_f32_dpp v6, v6, v6 quad_perm:[1,0,3,2] row_mask:0xf bank_mask:0xf bound_ctrl:1
	v_rcp_f32_e32 v4, v4
	v_rcp_f32_e32 v9, v9
	v_add_f32_dpp v6, v6, v6 quad_perm:[2,3,0,1] row_mask:0xf bank_mask:0xf bound_ctrl:1
	v_mov_b32_e32 v7, 0
	v_fma_f32 v4, v119, v4, v117
	v_add_f32_dpp v6, v6, v6 row_half_mirror row_mask:0xf bank_mask:0xf bound_ctrl:1
	v_fma_f32 v9, v120, v9, v118
	ds_write2st64_b32 v91, v4, v9 offset1:1
	v_add_f32_dpp v6, v6, v6 row_mirror row_mask:0xf bank_mask:0xf bound_ctrl:1
	v_and_b32_e32 v4, 0xffff0000, v0
	v_lshlrev_b32_e32 v9, 16, v0
	v_mov_b32_dpp v7, v6 row_bcast:15 row_mask:0xa bank_mask:0xf
	v_add_f32_e32 v6, v6, v7
	v_mov_b32_e32 v7, 0
	v_sub_f32_e32 v9, v9, v4
	ds_write2st64_b32 v93, v9, v4 offset0:128 offset1:160
	v_mov_b32_dpp v7, v6 row_bcast:31 row_mask:0xc bank_mask:0xf
	v_add_f32_e32 v6, v6, v7
	s_nop 0
	v_readlane_b32 s17, v6, 63
	s_and_saveexec_b64 s[20:21], s[6:7]
	s_nop 0
	v_mov_b32_e32 v6, s17
	ds_write_b32 v94, v6
	s_or_b64 exec, exec, s[20:21]
	v_and_b32_e32 v6, 0xffff0000, v121
	v_mul_f32_e32 v7, 0xbfb8aa3b, v6
	v_exp_f32_e32 v7, v7
	v_and_b32_e32 v10, 0xffff0000, v123
	v_mul_f32_e32 v10, 0xbfb8aa3b, v10
	v_and_b32_e32 v8, 0xffff0000, v122
	v_add_f32_e32 v7, 1.0, v7
	v_rcp_f32_e32 v7, v7
	v_mul_f32_e32 v9, 0xbfb8aa3b, v8
	v_exp_f32_e32 v9, v9
	v_mul_f32_e32 v7, v7, v6
	v_exp_f32_e32 v6, v10
	v_and_b32_e32 v10, 0xffff0000, v124
	v_mul_f32_e32 v10, 0xbfb8aa3b, v10
	v_exp_f32_e32 v10, v10
	v_add_f32_e32 v6, 1.0, v6
	v_add_f32_e32 v9, 1.0, v9
	v_rcp_f32_e32 v6, v6
	v_add_f32_e32 v10, 1.0, v10
	v_rcp_f32_e32 v10, v10
	v_rcp_f32_e32 v9, v9
	v_fma_f32 v6, v119, v6, v117
	v_fma_f32 v10, v120, v10, v118
	v_mul_f32_e32 v11, v9, v8
	ds_write2st64_b32 v95, v6, v10 offset1:1
	v_lshlrev_b32_e32 v6, 16, v1
	ds_write2st64_b32 v95, v7, v11 offset0:64 offset1:65
	v_sub_f32_e32 v4, v4, v6
	v_fmac_f32_e32 v7, v9, v8
	ds_write2st64_b32 v97, v4, v6 offset0:128 offset1:160
	s_nop 0
	v_add_f32_dpp v4, v7, v7 quad_perm:[1,0,3,2] row_mask:0xf bank_mask:0xf bound_ctrl:1
	v_mov_b32_e32 v7, 0
	s_nop 0
	v_add_f32_dpp v4, v4, v4 quad_perm:[2,3,0,1] row_mask:0xf bank_mask:0xf bound_ctrl:1
	s_nop 1
	v_add_f32_dpp v4, v4, v4 row_half_mirror row_mask:0xf bank_mask:0xf bound_ctrl:1
	s_nop 1
	v_add_f32_dpp v4, v4, v4 row_mirror row_mask:0xf bank_mask:0xf bound_ctrl:1
	s_nop 1
	v_mov_b32_dpp v7, v4 row_bcast:15 row_mask:0xa bank_mask:0xf
	v_add_f32_e32 v4, v4, v7
	v_mov_b32_e32 v7, 0
	s_nop 1
	v_mov_b32_dpp v7, v4 row_bcast:31 row_mask:0xc bank_mask:0xf
	v_add_f32_e32 v4, v4, v7
	s_nop 0
	v_readlane_b32 s17, v4, 63
	s_and_saveexec_b64 s[20:21], s[6:7]
	s_nop 0
	v_mov_b32_e32 v4, s17
	ds_write_b32 v98, v4
	s_or_b64 exec, exec, s[20:21]
	v_lshlrev_b32_e32 v4, 16, v125
	v_mul_f32_e32 v7, 0xbfb8aa3b, v4
	v_exp_f32_e32 v7, v7
	v_lshlrev_b32_e32 v10, 16, v127
	v_mul_f32_e32 v10, 0xbfb8aa3b, v10
	v_lshlrev_b32_e32 v8, 16, v126
	v_add_f32_e32 v7, 1.0, v7
	v_rcp_f32_e32 v7, v7
	v_mul_f32_e32 v9, 0xbfb8aa3b, v8
	v_exp_f32_e32 v9, v9
	v_mul_f32_e32 v7, v7, v4
	v_exp_f32_e32 v4, v10
	v_lshlrev_b32_e32 v10, 16, v128
	v_mul_f32_e32 v10, 0xbfb8aa3b, v10
	v_exp_f32_e32 v10, v10
	v_add_f32_e32 v4, 1.0, v4
	v_add_f32_e32 v9, 1.0, v9
	v_rcp_f32_e32 v4, v4
	v_add_f32_e32 v10, 1.0, v10
	v_rcp_f32_e32 v10, v10
	v_rcp_f32_e32 v9, v9
	v_fma_f32 v4, v119, v4, v117
	v_fma_f32 v10, v120, v10, v118
	v_mul_f32_e32 v11, v9, v8
	ds_write2st64_b32 v99, v4, v10 offset1:1
	v_and_b32_e32 v4, 0xffff0000, v1
	ds_write2st64_b32 v99, v7, v11 offset0:64 offset1:65
	v_sub_f32_e32 v6, v6, v4
	v_fmac_f32_e32 v7, v9, v8
	ds_write2st64_b32 v101, v6, v4 offset0:128 offset1:160
	s_nop 0
	v_add_f32_dpp v6, v7, v7 quad_perm:[1,0,3,2] row_mask:0xf bank_mask:0xf bound_ctrl:1
	v_mov_b32_e32 v7, 0
	s_nop 0
	v_add_f32_dpp v6, v6, v6 quad_perm:[2,3,0,1] row_mask:0xf bank_mask:0xf bound_ctrl:1
	s_nop 1
	v_add_f32_dpp v6, v6, v6 row_half_mirror row_mask:0xf bank_mask:0xf bound_ctrl:1
	s_nop 1
	v_add_f32_dpp v6, v6, v6 row_mirror row_mask:0xf bank_mask:0xf bound_ctrl:1
	s_nop 1
	v_mov_b32_dpp v7, v6 row_bcast:15 row_mask:0xa bank_mask:0xf
	v_add_f32_e32 v6, v6, v7
	v_mov_b32_e32 v7, 0
	s_nop 1
	v_mov_b32_dpp v7, v6 row_bcast:31 row_mask:0xc bank_mask:0xf
	v_add_f32_e32 v6, v6, v7
	s_nop 0
	v_readlane_b32 s17, v6, 63
	s_and_saveexec_b64 s[20:21], s[6:7]
	s_nop 0
	v_mov_b32_e32 v6, s17
	ds_write_b32 v102, v6
	s_or_b64 exec, exec, s[20:21]
	v_and_b32_e32 v6, 0xffff0000, v125
	v_mul_f32_e32 v7, 0xbfb8aa3b, v6
	v_exp_f32_e32 v7, v7
	v_and_b32_e32 v10, 0xffff0000, v127
	v_mul_f32_e32 v10, 0xbfb8aa3b, v10
	v_and_b32_e32 v8, 0xffff0000, v126
	v_add_f32_e32 v7, 1.0, v7
	v_rcp_f32_e32 v7, v7
	v_mul_f32_e32 v9, 0xbfb8aa3b, v8
	v_exp_f32_e32 v9, v9
	v_mul_f32_e32 v6, v7, v6
	v_exp_f32_e32 v7, v10
	v_and_b32_e32 v10, 0xffff0000, v128
	v_mul_f32_e32 v10, 0xbfb8aa3b, v10
	v_exp_f32_e32 v10, v10
	v_add_f32_e32 v7, 1.0, v7
	v_add_f32_e32 v9, 1.0, v9
	v_rcp_f32_e32 v7, v7
	v_add_f32_e32 v10, 1.0, v10
	v_rcp_f32_e32 v10, v10
	v_rcp_f32_e32 v9, v9
	v_fma_f32 v7, v119, v7, v117
	v_fma_f32 v10, v120, v10, v118
	v_mul_f32_e32 v11, v9, v8
	ds_write2st64_b32 v103, v7, v10 offset1:1
	v_lshlrev_b32_e32 v7, 16, v2
	ds_write2st64_b32 v103, v6, v11 offset0:64 offset1:65
	v_sub_f32_e32 v4, v4, v7
	v_fmac_f32_e32 v6, v9, v8
	ds_write2st64_b32 v105, v4, v7 offset0:128 offset1:160
	s_nop 0
	v_add_f32_dpp v4, v6, v6 quad_perm:[1,0,3,2] row_mask:0xf bank_mask:0xf bound_ctrl:1
	v_mov_b32_e32 v6, 0
	s_nop 0
	v_add_f32_dpp v4, v4, v4 quad_perm:[2,3,0,1] row_mask:0xf bank_mask:0xf bound_ctrl:1
	s_nop 1
	v_add_f32_dpp v4, v4, v4 row_half_mirror row_mask:0xf bank_mask:0xf bound_ctrl:1
	s_nop 1
	v_add_f32_dpp v4, v4, v4 row_mirror row_mask:0xf bank_mask:0xf bound_ctrl:1
	s_nop 1
	v_mov_b32_dpp v6, v4 row_bcast:15 row_mask:0xa bank_mask:0xf
	v_add_f32_e32 v4, v4, v6
	v_mov_b32_e32 v6, 0
	s_nop 1
	v_mov_b32_dpp v6, v4 row_bcast:31 row_mask:0xc bank_mask:0xf
	v_add_f32_e32 v4, v4, v6
	s_nop 0
	v_readlane_b32 s17, v4, 63
	s_and_saveexec_b64 s[20:21], s[6:7]
	s_cbranch_execz .LBB0_2156
	v_mov_b32_e32 v4, s17
	ds_write_b32 v106, v4
	s_branch .LBB0_2156

; __device__ __forceinline__ void phase_rwkv(KP P, int l_, unsigned char* shm) {
;     ...
;                 if (c + 1 < NC) { RW_PREP(c + 1); if (c + 2 < NC) RW_LOAD(c + 2); }
;             }
;             __syncthreads();
;         }
.LBB0_2488:
.LBB0_2489:
	s_add_i32 s42, s42, 1
	s_xor_b64 s[78:79], s[78:79], -1
	s_cmp_eq_u32 s42, 64
	v_add_u32_e32 v175, 0x2000, v175
	s_waitcnt lgkmcnt(0)
	s_barrier
	s_cbranch_scc1 .LBB0_2526

.LBB0_2493:
.LBB0_2494:
	s_cmp_eq_u32 s42, 0
	s_cbranch_scc1 .Lrw_nopack
	s_waitcnt vmcnt(8)
	v_perm_b32 v215, v62, v61, s82
	v_perm_b32 v222, v42, v60, s82
	v_perm_b32 v226, v46, v44, s82
	v_perm_b32 v216, v64, v63, s82
	v_perm_b32 v221, v41, v40, s82
	v_perm_b32 v223, v45, v43, s82
	v_perm_b32 v224, v50, v47, s82
	v_perm_b32 v227, v51, v48, s82
	v_perm_b32 v217, v52, v49, s82
	v_perm_b32 v225, v56, v53, s82
	v_perm_b32 v242, v57, v54, s82
	v_perm_b32 v218, v58, v55, s82
.Lrw_nopack:
	s_andn2_b64 vcc, exec, s[72:73]
	v_mov_b32_e32 v0, v176
	v_mov_b32_e32 v1, v214
	v_mov_b32_e32 v2, v219
	v_mov_b32_e32 v3, v177
	v_mov_b32_e32 v9, v190
	v_mov_b32_e32 v10, v191
	v_mov_b32_e32 v11, v192
	v_mov_b32_e32 v21, v193
	v_mov_b32_e32 v28, v194
	v_mov_b32_e32 v35, v195
	v_mov_b32_e32 v38, v196
	v_mov_b32_e32 v4, v197
	v_mov_b32_e32 v8, v198
	v_mov_b32_e32 v12, v199
	v_mov_b32_e32 v13, v200
	v_mov_b32_e32 v30, v201
	v_mov_b32_e32 v31, v202
	v_mov_b32_e32 v33, v203
	v_mov_b32_e32 v37, v204
	v_mov_b32_e32 v6, v205
	v_mov_b32_e32 v7, v206
	v_mov_b32_e32 v14, v207
	v_mov_b32_e32 v15, v208
	v_mov_b32_e32 v32, v209
	v_mov_b32_e32 v34, v210
	v_mov_b32_e32 v36, v211
	v_mov_b32_e32 v39, v212
	s_cbranch_vccnz .LBB0_2513
	v_and_b32_e32 v2, 0xffff0000, v222
	v_lshlrev_b32_e32 v3, 16, v222
	v_sub_f32_e32 v3, v3, v2
	v_fma_f32 v3, v245, v3, v2
	v_mul_f32_e32 v9, v247, v3
	v_mul_f32_e32 v10, v9, v9
	s_add_i32 s0, s42, 1
	s_and_b32 s1, s0, 1
	v_mov_b32_dpp v10, v10 quad_perm:[1,0,3,2] row_mask:0xf bank_mask:0xf bound_ctrl:1
	v_fmac_f32_e32 v10, v9, v9
	s_mul_i32 s43, s1, 0xa000
	s_add_i32 s52, s43, 0
	v_add_f32_dpp v10, v10, v10 quad_perm:[2,3,0,1] row_mask:0xf bank_mask:0xf bound_ctrl:1
	s_mul_hi_u32 s43, s0, 0xaaaaaaab
	v_lshlrev_b32_e32 v8, 16, v197
	v_add_f32_dpp v10, v10, v10 row_half_mirror row_mask:0xf bank_mask:0xf bound_ctrl:1
	v_mov_b32_e32 v11, 0
	s_lshr_b32 s43, s43, 1
	v_add_f32_dpp v10, v10, v10 row_mirror row_mask:0xf bank_mask:0xf bound_ctrl:1
	v_add_f32_e32 v8, v251, v8
	s_mul_i32 s43, s43, 3
	v_mov_b32_dpp v11, v10 row_bcast:15 row_mask:0xa bank_mask:0xf
	v_mul_f32_e32 v8, 0xbfb8aa3b, v8
	v_add_f32_e32 v10, v10, v11
	v_mov_b32_e32 v11, 0
	s_sub_i32 s0, s0, s43
	v_exp_f32_e32 v8, v8
	v_mov_b32_dpp v11, v10 row_bcast:31 row_mask:0xc bank_mask:0xf
	s_lshl_b32 s43, s0, 13
	s_lshl_b32 s0, s0, 7
	v_add_f32_e32 v10, v10, v11
	s_add_i32 vcc_lo, s43, 0
	s_add_i32 s43, s0, 0
	v_readlane_b32 s0, v10, 63
	v_add_f32_e32 v8, 1.0, v8
	v_rcp_f32_e32 v8, v8
	v_max_f32_e64 v10, s0, s0
	v_max_f32_e32 v10, 0x179abe15, v10
	v_rsq_f32_e32 v10, v10
	v_lshlrev_b32_e32 v6, 16, v205
	v_add_f32_e32 v6, v250, v6
	v_mul_f32_e32 v6, 0xbfb8aa3b, v6
	v_and_b32_e32 v4, 0xffff0000, v221
	v_lshlrev_b32_e32 v1, 16, v221
	v_exp_f32_e32 v6, v6
	v_mul_f32_e32 v9, v9, v10
	v_add_f32_e32 v10, -1.0, v8
	v_sub_f32_e32 v1, v1, v4
	v_fma_f32 v10, v248, v10, 1.0
	v_fma_f32 v1, v244, v1, v4
	v_mul_f32_e32 v3, v10, v3
	v_mul_f32_e32 v10, v1, v3
	v_add_f32_e32 v6, 1.0, v6
	v_mul_f32_e32 v11, v249, v10
	v_rcp_f32_e32 v6, v6
	s_lshl_b32 s1, s1, 13
	v_mov_b32_dpp v11, v11 quad_perm:[1,0,3,2] row_mask:0xf bank_mask:0xf bound_ctrl:1
	v_fmac_f32_e32 v11, v249, v10
	v_mul_f32_e32 v6, 0xbf1b4598, v6
	v_mul_f32_e32 v6, 0x3fb8aa3b, v6
	v_add_f32_dpp v10, v11, v11 quad_perm:[2,3,0,1] row_mask:0xf bank_mask:0xf bound_ctrl:1
	v_mov_b32_e32 v11, 0
	v_exp_f32_e32 v6, v6
	v_add_f32_dpp v10, v10, v10 row_half_mirror row_mask:0xf bank_mask:0xf bound_ctrl:1
	v_and_b32_e32 v0, 0xffff0000, v215
	v_lshlrev_b32_e32 v7, 16, v215
	v_add_f32_dpp v10, v10, v10 row_mirror row_mask:0xf bank_mask:0xf bound_ctrl:1
	s_add_i32 vcc_lo, vcc_lo, 0x14000
	s_add_i32 vcc_hi, s1, 0
	v_mov_b32_dpp v11, v10 row_bcast:15 row_mask:0xa bank_mask:0xf
	v_add_f32_e32 v10, v10, v11
	v_mov_b32_e32 v11, 0
	v_sub_f32_e32 v7, v7, v0
	s_add_i32 vcc_hi, vcc_hi, 0x1a000
	v_mov_b32_dpp v11, v10 row_bcast:31 row_mask:0xc bank_mask:0xf
	v_add_f32_e32 v10, v10, v11
	v_fma_f32 v7, v246, v7, v0
	v_readlane_b32 s50, v10, 63
	v_add_u32_e32 v10, s52, v124
	ds_write2st64_b32 v10, v6, v9 offset1:32
	v_mul_f32_e32 v6, v8, v9
	ds_write2st64_b32 v10, v6, v3 offset0:64 offset1:96
	ds_write_b32 v10, v1 offset:32768
	v_add_u32_e32 v1, vcc_lo, v124
	s_add_i32 s43, s43, 0x22000
	ds_write_b32 v1, v7
	v_lshlrev_b32_e32 v1, 16, v177
	v_add_u32_e32 v3, vcc_hi, v124
	ds_write_b32 v3, v1
	s_and_saveexec_b64 s[72:73], s[4:5]
	s_lshl_b32 s0, s38, 2
	s_add_i32 s0, s43, s0
	v_mov_b32_e32 v1, s0
	v_mov_b32_e32 v3, s50
	ds_write_b32 v1, v3
	s_or_b64 exec, exec, s[72:73]
	v_lshlrev_b32_e32 v3, 16, v226
	v_sub_f32_e32 v2, v2, v3
	v_fma_f32 v2, v245, v2, v3
	v_mul_f32_e32 v9, v247, v2
	v_mul_f32_e32 v10, v9, v9
	v_lshlrev_b32_e32 v8, 16, v198
	v_mov_b32_e32 v11, 0
	v_mov_b32_dpp v10, v10 quad_perm:[1,0,3,2] row_mask:0xf bank_mask:0xf bound_ctrl:1
	v_fmac_f32_e32 v10, v9, v9
	v_add_f32_e32 v8, v251, v8
	v_mul_f32_e32 v8, 0xbfb8aa3b, v8
	v_add_f32_dpp v10, v10, v10 quad_perm:[2,3,0,1] row_mask:0xf bank_mask:0xf bound_ctrl:1
	v_exp_f32_e32 v8, v8
	v_lshlrev_b32_e32 v7, 16, v206
	v_add_f32_dpp v10, v10, v10 row_half_mirror row_mask:0xf bank_mask:0xf bound_ctrl:1
	v_add_f32_e32 v7, v250, v7
	v_add_f32_e32 v8, 1.0, v8
	v_add_f32_dpp v10, v10, v10 row_mirror row_mask:0xf bank_mask:0xf bound_ctrl:1
	v_rcp_f32_e32 v8, v8
	v_mul_f32_e32 v7, 0xbfb8aa3b, v7
	v_mov_b32_dpp v11, v10 row_bcast:15 row_mask:0xa bank_mask:0xf
	v_add_f32_e32 v10, v10, v11
	v_mov_b32_e32 v11, 0
	v_lshlrev_b32_e32 v6, 16, v223
	v_exp_f32_e32 v7, v7
	v_mov_b32_dpp v11, v10 row_bcast:31 row_mask:0xc bank_mask:0xf
	v_add_f32_e32 v10, v10, v11
	v_sub_f32_e32 v4, v4, v6
	v_readlane_b32 s0, v10, 63
	v_fma_f32 v4, v244, v4, v6
	v_add_f32_e32 v7, 1.0, v7
	v_max_f32_e64 v10, s0, s0
	v_max_f32_e32 v10, 0x179abe15, v10
	v_rsq_f32_e32 v10, v10
	v_rcp_f32_e32 v7, v7
	v_lshlrev_b32_e32 v1, 16, v216
	v_sub_f32_e32 v0, v0, v1
	v_mul_f32_e32 v9, v9, v10
	v_add_f32_e32 v10, -1.0, v8
	v_fma_f32 v10, v248, v10, 1.0
	v_mul_f32_e32 v2, v10, v2
	v_mul_f32_e32 v10, v4, v2
	v_mul_f32_e32 v11, v249, v10
	v_mul_f32_e32 v7, 0xbf1b4598, v7
	v_mul_f32_e32 v7, 0x3fb8aa3b, v7
	v_mov_b32_dpp v11, v11 quad_perm:[1,0,3,2] row_mask:0xf bank_mask:0xf bound_ctrl:1
	v_fmac_f32_e32 v11, v249, v10
	v_exp_f32_e32 v7, v7
	v_fma_f32 v0, v246, v0, v1
	v_add_f32_dpp v10, v11, v11 quad_perm:[2,3,0,1] row_mask:0xf bank_mask:0xf bound_ctrl:1
	v_mov_b32_e32 v11, 0
	s_nop 0
	v_add_f32_dpp v10, v10, v10 row_half_mirror row_mask:0xf bank_mask:0xf bound_ctrl:1
	s_nop 1
	v_add_f32_dpp v10, v10, v10 row_mirror row_mask:0xf bank_mask:0xf bound_ctrl:1
	s_nop 1
	v_mov_b32_dpp v11, v10 row_bcast:15 row_mask:0xa bank_mask:0xf
	v_add_f32_e32 v10, v10, v11
	v_mov_b32_e32 v11, 0
	s_nop 1
	v_mov_b32_dpp v11, v10 row_bcast:31 row_mask:0xc bank_mask:0xf
	v_add_f32_e32 v10, v10, v11
	s_nop 0
	v_readlane_b32 s50, v10, 63
	v_add_u32_e32 v10, s52, v128
	ds_write2st64_b32 v10, v7, v9 offset1:32
	v_mul_f32_e32 v7, v8, v9
	ds_write2st64_b32 v10, v7, v2 offset0:64 offset1:96
	ds_write_b32 v10, v4 offset:32768
	v_add_u32_e32 v2, vcc_lo, v128
	ds_write_b32 v2, v0
	v_lshlrev_b32_e32 v0, 16, v190
	v_add_u32_e32 v2, vcc_hi, v128
	ds_write_b32 v2, v0
	s_and_saveexec_b64 s[72:73], s[4:5]
	s_lshl_b32 s0, s38, 2
	s_add_i32 s0, s43, s0
	v_mov_b32_e32 v0, s0
	v_mov_b32_e32 v2, s50
	ds_write_b32 v0, v2 offset:4
	s_or_b64 exec, exec, s[72:73]
	v_and_b32_e32 v2, 0xffff0000, v226
	v_sub_f32_e32 v3, v3, v2
	v_fma_f32 v3, v245, v3, v2
	v_mul_f32_e32 v9, v247, v3
	v_mul_f32_e32 v10, v9, v9
	v_lshlrev_b32_e32 v8, 16, v199
	v_mov_b32_e32 v11, 0
	v_mov_b32_dpp v10, v10 quad_perm:[1,0,3,2] row_mask:0xf bank_mask:0xf bound_ctrl:1
	v_fmac_f32_e32 v10, v9, v9
	v_add_f32_e32 v8, v251, v8
	v_mul_f32_e32 v8, 0xbfb8aa3b, v8
	v_add_f32_dpp v10, v10, v10 quad_perm:[2,3,0,1] row_mask:0xf bank_mask:0xf bound_ctrl:1
	v_exp_f32_e32 v8, v8
	v_lshlrev_b32_e32 v7, 16, v207
	v_add_f32_dpp v10, v10, v10 row_half_mirror row_mask:0xf bank_mask:0xf bound_ctrl:1
	v_add_f32_e32 v7, v250, v7
	v_add_f32_e32 v8, 1.0, v8
	v_add_f32_dpp v10, v10, v10 row_mirror row_mask:0xf bank_mask:0xf bound_ctrl:1
	v_rcp_f32_e32 v8, v8
	v_mul_f32_e32 v7, 0xbfb8aa3b, v7
	v_mov_b32_dpp v11, v10 row_bcast:15 row_mask:0xa bank_mask:0xf
	v_add_f32_e32 v10, v10, v11
	v_mov_b32_e32 v11, 0
	v_and_b32_e32 v4, 0xffff0000, v223
	v_exp_f32_e32 v7, v7
	v_mov_b32_dpp v11, v10 row_bcast:31 row_mask:0xc bank_mask:0xf
	v_add_f32_e32 v10, v10, v11
	v_sub_f32_e32 v6, v6, v4
	v_readlane_b32 s0, v10, 63
	v_fma_f32 v6, v244, v6, v4
	v_add_f32_e32 v7, 1.0, v7
	v_max_f32_e64 v10, s0, s0
	v_max_f32_e32 v10, 0x179abe15, v10
	v_rsq_f32_e32 v10, v10
	v_rcp_f32_e32 v7, v7
	v_and_b32_e32 v0, 0xffff0000, v216
	v_sub_f32_e32 v1, v1, v0
	v_mul_f32_e32 v9, v9, v10
	v_add_f32_e32 v10, -1.0, v8
	v_fma_f32 v10, v248, v10, 1.0
	v_mul_f32_e32 v3, v10, v3
	v_mul_f32_e32 v10, v6, v3
	v_mul_f32_e32 v11, v249, v10
	v_mul_f32_e32 v7, 0xbf1b4598, v7
	v_mul_f32_e32 v7, 0x3fb8aa3b, v7
	v_mov_b32_dpp v11, v11 quad_perm:[1,0,3,2] row_mask:0xf bank_mask:0xf bound_ctrl:1
	v_fmac_f32_e32 v11, v249, v10
	v_exp_f32_e32 v7, v7
	v_fma_f32 v1, v246, v1, v0
	v_add_f32_dpp v10, v11, v11 quad_perm:[2,3,0,1] row_mask:0xf bank_mask:0xf bound_ctrl:1
	v_mov_b32_e32 v11, 0
	s_nop 0
	v_add_f32_dpp v10, v10, v10 row_half_mirror row_mask:0xf bank_mask:0xf bound_ctrl:1
	s_nop 1
	v_add_f32_dpp v10, v10, v10 row_mirror row_mask:0xf bank_mask:0xf bound_ctrl:1
	s_nop 1
	v_mov_b32_dpp v11, v10 row_bcast:15 row_mask:0xa bank_mask:0xf
	v_add_f32_e32 v10, v10, v11
	v_mov_b32_e32 v11, 0
	s_nop 1
	v_mov_b32_dpp v11, v10 row_bcast:31 row_mask:0xc bank_mask:0xf
	v_add_f32_e32 v10, v10, v11
	s_nop 0
	v_readlane_b32 s50, v10, 63
	v_add_u32_e32 v10, s52, v132
	ds_write2st64_b32 v10, v7, v9 offset1:32
	v_mul_f32_e32 v7, v8, v9
	ds_write2st64_b32 v10, v7, v3 offset0:64 offset1:96
	ds_write_b32 v10, v6 offset:32768
	v_add_u32_e32 v3, vcc_lo, v132
	ds_write_b32 v3, v1
	v_lshlrev_b32_e32 v1, 16, v191
	v_add_u32_e32 v3, vcc_hi, v132
	ds_write_b32 v3, v1
	s_and_saveexec_b64 s[72:73], s[4:5]
	s_lshl_b32 s0, s38, 2
	s_add_i32 s0, s43, s0
	v_mov_b32_e32 v1, s0
	v_mov_b32_e32 v3, s50
	ds_write_b32 v1, v3 offset:8
	s_or_b64 exec, exec, s[72:73]
	v_lshlrev_b32_e32 v3, 16, v227
	v_sub_f32_e32 v2, v2, v3
	v_fma_f32 v2, v245, v2, v3
	v_mul_f32_e32 v9, v247, v2
	v_mul_f32_e32 v10, v9, v9
	v_lshlrev_b32_e32 v8, 16, v200
	v_mov_b32_e32 v11, 0
	v_mov_b32_dpp v10, v10 quad_perm:[1,0,3,2] row_mask:0xf bank_mask:0xf bound_ctrl:1
	v_fmac_f32_e32 v10, v9, v9
	v_add_f32_e32 v8, v251, v8
	v_mul_f32_e32 v8, 0xbfb8aa3b, v8
	v_add_f32_dpp v10, v10, v10 quad_perm:[2,3,0,1] row_mask:0xf bank_mask:0xf bound_ctrl:1
	v_exp_f32_e32 v8, v8
	v_lshlrev_b32_e32 v7, 16, v208
	v_add_f32_dpp v10, v10, v10 row_half_mirror row_mask:0xf bank_mask:0xf bound_ctrl:1
	v_add_f32_e32 v7, v250, v7
	v_add_f32_e32 v8, 1.0, v8
	v_add_f32_dpp v10, v10, v10 row_mirror row_mask:0xf bank_mask:0xf bound_ctrl:1
	v_rcp_f32_e32 v8, v8
	v_mul_f32_e32 v7, 0xbfb8aa3b, v7
	v_mov_b32_dpp v11, v10 row_bcast:15 row_mask:0xa bank_mask:0xf
	v_add_f32_e32 v10, v10, v11
	v_mov_b32_e32 v11, 0
	v_lshlrev_b32_e32 v6, 16, v224
	v_exp_f32_e32 v7, v7
	v_mov_b32_dpp v11, v10 row_bcast:31 row_mask:0xc bank_mask:0xf
	v_add_f32_e32 v10, v10, v11
	v_sub_f32_e32 v4, v4, v6
	v_readlane_b32 s0, v10, 63
	v_fma_f32 v4, v244, v4, v6
	v_add_f32_e32 v7, 1.0, v7
	v_max_f32_e64 v10, s0, s0
	v_max_f32_e32 v10, 0x179abe15, v10
	v_rsq_f32_e32 v10, v10
	v_rcp_f32_e32 v7, v7
	v_lshlrev_b32_e32 v1, 16, v217
	v_sub_f32_e32 v0, v0, v1
	v_mul_f32_e32 v9, v9, v10
	v_add_f32_e32 v10, -1.0, v8
	v_fma_f32 v10, v248, v10, 1.0
	v_mul_f32_e32 v2, v10, v2
	v_mul_f32_e32 v10, v4, v2
	v_mul_f32_e32 v11, v249, v10
	v_mul_f32_e32 v7, 0xbf1b4598, v7
	v_mul_f32_e32 v7, 0x3fb8aa3b, v7
	v_mov_b32_dpp v11, v11 quad_perm:[1,0,3,2] row_mask:0xf bank_mask:0xf bound_ctrl:1
	v_fmac_f32_e32 v11, v249, v10
	v_exp_f32_e32 v7, v7
	v_fma_f32 v0, v246, v0, v1
	v_add_f32_dpp v10, v11, v11 quad_perm:[2,3,0,1] row_mask:0xf bank_mask:0xf bound_ctrl:1
	v_mov_b32_e32 v11, 0
	s_nop 0
	v_add_f32_dpp v10, v10, v10 row_half_mirror row_mask:0xf bank_mask:0xf bound_ctrl:1
	s_nop 1
	v_add_f32_dpp v10, v10, v10 row_mirror row_mask:0xf bank_mask:0xf bound_ctrl:1
	s_nop 1
	v_mov_b32_dpp v11, v10 row_bcast:15 row_mask:0xa bank_mask:0xf
	v_add_f32_e32 v10, v10, v11
	v_mov_b32_e32 v11, 0
	s_nop 1
	v_mov_b32_dpp v11, v10 row_bcast:31 row_mask:0xc bank_mask:0xf
	v_add_f32_e32 v10, v10, v11
	s_nop 0
	v_readlane_b32 s50, v10, 63
	v_add_u32_e32 v10, s52, v136
	ds_write2st64_b32 v10, v7, v9 offset1:32
	v_mul_f32_e32 v7, v8, v9
	ds_write2st64_b32 v10, v7, v2 offset0:64 offset1:96
	ds_write_b32 v10, v4 offset:32768
	v_add_u32_e32 v2, vcc_lo, v136
	ds_write_b32 v2, v0
	v_lshlrev_b32_e32 v0, 16, v192
	v_add_u32_e32 v2, vcc_hi, v136
	ds_write_b32 v2, v0
	s_and_saveexec_b64 s[72:73], s[4:5]
	s_lshl_b32 s0, s38, 2
	s_add_i32 s0, s43, s0
	v_mov_b32_e32 v0, s0
	v_mov_b32_e32 v2, s50
	ds_write_b32 v0, v2 offset:12
	s_or_b64 exec, exec, s[72:73]
	v_and_b32_e32 v2, 0xffff0000, v227
	v_sub_f32_e32 v3, v3, v2
	v_fma_f32 v3, v245, v3, v2
	v_mul_f32_e32 v9, v247, v3
	v_mul_f32_e32 v10, v9, v9
	v_lshlrev_b32_e32 v8, 16, v201
	v_mov_b32_e32 v11, 0
	v_mov_b32_dpp v10, v10 quad_perm:[1,0,3,2] row_mask:0xf bank_mask:0xf bound_ctrl:1
	v_fmac_f32_e32 v10, v9, v9
	v_add_f32_e32 v8, v251, v8
	v_mul_f32_e32 v8, 0xbfb8aa3b, v8
	v_add_f32_dpp v10, v10, v10 quad_perm:[2,3,0,1] row_mask:0xf bank_mask:0xf bound_ctrl:1
	v_exp_f32_e32 v8, v8
	v_lshlrev_b32_e32 v7, 16, v209
	v_add_f32_dpp v10, v10, v10 row_half_mirror row_mask:0xf bank_mask:0xf bound_ctrl:1
	v_add_f32_e32 v7, v250, v7
	v_add_f32_e32 v8, 1.0, v8
	v_add_f32_dpp v10, v10, v10 row_mirror row_mask:0xf bank_mask:0xf bound_ctrl:1
	v_rcp_f32_e32 v8, v8
	v_mul_f32_e32 v7, 0xbfb8aa3b, v7
	v_mov_b32_dpp v11, v10 row_bcast:15 row_mask:0xa bank_mask:0xf
	v_add_f32_e32 v10, v10, v11
	v_mov_b32_e32 v11, 0
	v_and_b32_e32 v4, 0xffff0000, v224
	v_exp_f32_e32 v7, v7
	v_mov_b32_dpp v11, v10 row_bcast:31 row_mask:0xc bank_mask:0xf
	v_add_f32_e32 v10, v10, v11
	v_sub_f32_e32 v6, v6, v4
	v_readlane_b32 s0, v10, 63
	v_fma_f32 v6, v244, v6, v4
	v_add_f32_e32 v7, 1.0, v7
	v_max_f32_e64 v10, s0, s0
	v_max_f32_e32 v10, 0x179abe15, v10
	v_rsq_f32_e32 v10, v10
	v_rcp_f32_e32 v7, v7
	v_and_b32_e32 v0, 0xffff0000, v217
	v_sub_f32_e32 v1, v1, v0
	v_mul_f32_e32 v9, v9, v10
	v_add_f32_e32 v10, -1.0, v8
	v_fma_f32 v10, v248, v10, 1.0
	v_mul_f32_e32 v3, v10, v3
	v_mul_f32_e32 v10, v6, v3
	v_mul_f32_e32 v11, v249, v10
	v_mul_f32_e32 v7, 0xbf1b4598, v7
	v_mul_f32_e32 v7, 0x3fb8aa3b, v7
	v_mov_b32_dpp v11, v11 quad_perm:[1,0,3,2] row_mask:0xf bank_mask:0xf bound_ctrl:1
	v_fmac_f32_e32 v11, v249, v10
	v_exp_f32_e32 v7, v7
	v_fma_f32 v1, v246, v1, v0
	v_add_f32_dpp v10, v11, v11 quad_perm:[2,3,0,1] row_mask:0xf bank_mask:0xf bound_ctrl:1
	v_mov_b32_e32 v11, 0
	s_nop 0
	v_add_f32_dpp v10, v10, v10 row_half_mirror row_mask:0xf bank_mask:0xf bound_ctrl:1
	s_nop 1
	v_add_f32_dpp v10, v10, v10 row_mirror row_mask:0xf bank_mask:0xf bound_ctrl:1
	s_nop 1
	v_mov_b32_dpp v11, v10 row_bcast:15 row_mask:0xa bank_mask:0xf
	v_add_f32_e32 v10, v10, v11
	v_mov_b32_e32 v11, 0
	s_nop 1
	v_mov_b32_dpp v11, v10 row_bcast:31 row_mask:0xc bank_mask:0xf
	v_add_f32_e32 v10, v10, v11
	s_nop 0
	v_readlane_b32 s50, v10, 63
	v_add_u32_e32 v10, s52, v140
	ds_write2st64_b32 v10, v7, v9 offset1:32
	v_mul_f32_e32 v7, v8, v9
	ds_write2st64_b32 v10, v7, v3 offset0:64 offset1:96
	ds_write_b32 v10, v6 offset:32768
	v_add_u32_e32 v3, vcc_lo, v140
	ds_write_b32 v3, v1
	v_lshlrev_b32_e32 v1, 16, v193
	v_add_u32_e32 v3, vcc_hi, v140
	ds_write_b32 v3, v1
	s_and_saveexec_b64 s[72:73], s[4:5]
	s_lshl_b32 s0, s38, 2
	s_add_i32 s0, s43, s0
	v_mov_b32_e32 v1, s0
	v_mov_b32_e32 v3, s50
	ds_write_b32 v1, v3 offset:16
	s_or_b64 exec, exec, s[72:73]
	v_lshlrev_b32_e32 v3, 16, v242
	v_sub_f32_e32 v2, v2, v3
	v_fma_f32 v2, v245, v2, v3
	v_mul_f32_e32 v9, v247, v2
	v_mul_f32_e32 v10, v9, v9
	v_lshlrev_b32_e32 v8, 16, v202
	v_mov_b32_e32 v11, 0
	v_mov_b32_dpp v10, v10 quad_perm:[1,0,3,2] row_mask:0xf bank_mask:0xf bound_ctrl:1
	v_fmac_f32_e32 v10, v9, v9
	v_add_f32_e32 v8, v251, v8
	v_mul_f32_e32 v8, 0xbfb8aa3b, v8
	v_add_f32_dpp v10, v10, v10 quad_perm:[2,3,0,1] row_mask:0xf bank_mask:0xf bound_ctrl:1
	v_exp_f32_e32 v8, v8
	v_lshlrev_b32_e32 v7, 16, v210
	v_add_f32_dpp v10, v10, v10 row_half_mirror row_mask:0xf bank_mask:0xf bound_ctrl:1
	v_add_f32_e32 v7, v250, v7
	v_add_f32_e32 v8, 1.0, v8
	v_add_f32_dpp v10, v10, v10 row_mirror row_mask:0xf bank_mask:0xf bound_ctrl:1
	v_rcp_f32_e32 v8, v8
	v_mul_f32_e32 v7, 0xbfb8aa3b, v7
	v_mov_b32_dpp v11, v10 row_bcast:15 row_mask:0xa bank_mask:0xf
	v_add_f32_e32 v10, v10, v11
	v_mov_b32_e32 v11, 0
	v_lshlrev_b32_e32 v6, 16, v225
	v_exp_f32_e32 v7, v7
	v_mov_b32_dpp v11, v10 row_bcast:31 row_mask:0xc bank_mask:0xf
	v_add_f32_e32 v10, v10, v11
	v_sub_f32_e32 v4, v4, v6
	v_readlane_b32 s0, v10, 63
	v_fma_f32 v4, v244, v4, v6
	v_add_f32_e32 v7, 1.0, v7
	v_max_f32_e64 v10, s0, s0
	v_max_f32_e32 v10, 0x179abe15, v10
	v_rsq_f32_e32 v10, v10
	v_rcp_f32_e32 v7, v7
	v_lshlrev_b32_e32 v1, 16, v218
	v_sub_f32_e32 v0, v0, v1
	v_mul_f32_e32 v9, v9, v10
	v_add_f32_e32 v10, -1.0, v8
	v_fma_f32 v10, v248, v10, 1.0
	v_mul_f32_e32 v2, v10, v2
	v_mul_f32_e32 v10, v4, v2
	v_mul_f32_e32 v11, v249, v10
	v_mul_f32_e32 v7, 0xbf1b4598, v7
	v_mul_f32_e32 v7, 0x3fb8aa3b, v7
	v_mov_b32_dpp v11, v11 quad_perm:[1,0,3,2] row_mask:0xf bank_mask:0xf bound_ctrl:1
	v_fmac_f32_e32 v11, v249, v10
	v_exp_f32_e32 v7, v7
	v_fma_f32 v0, v246, v0, v1
	v_add_f32_dpp v10, v11, v11 quad_perm:[2,3,0,1] row_mask:0xf bank_mask:0xf bound_ctrl:1
	v_mov_b32_e32 v11, 0
	s_nop 0
	v_add_f32_dpp v10, v10, v10 row_half_mirror row_mask:0xf bank_mask:0xf bound_ctrl:1
	s_nop 1
	v_add_f32_dpp v10, v10, v10 row_mirror row_mask:0xf bank_mask:0xf bound_ctrl:1
	s_nop 1
	v_mov_b32_dpp v11, v10 row_bcast:15 row_mask:0xa bank_mask:0xf
	v_add_f32_e32 v10, v10, v11
	v_mov_b32_e32 v11, 0
	s_nop 1
	v_mov_b32_dpp v11, v10 row_bcast:31 row_mask:0xc bank_mask:0xf
	v_add_f32_e32 v10, v10, v11
	s_nop 0
	v_readlane_b32 s50, v10, 63
	v_add_u32_e32 v10, s52, v144
	ds_write2st64_b32 v10, v7, v9 offset1:32
	v_mul_f32_e32 v7, v8, v9
	ds_write2st64_b32 v10, v7, v2 offset0:64 offset1:96
	ds_write_b32 v10, v4 offset:32768
	v_add_u32_e32 v2, vcc_lo, v144
	ds_write_b32 v2, v0
	v_lshlrev_b32_e32 v0, 16, v194
	v_add_u32_e32 v2, vcc_hi, v144
	ds_write_b32 v2, v0
	s_and_saveexec_b64 s[72:73], s[4:5]
	s_lshl_b32 s0, s38, 2
	s_add_i32 s0, s43, s0
	v_mov_b32_e32 v0, s0
	v_mov_b32_e32 v2, s50
	ds_write_b32 v0, v2 offset:20
	s_or_b64 exec, exec, s[72:73]
	v_and_b32_e32 v2, 0xffff0000, v242
	v_sub_f32_e32 v3, v3, v2
	v_fma_f32 v3, v245, v3, v2
	v_mul_f32_e32 v9, v247, v3
	v_mul_f32_e32 v10, v9, v9
	v_lshlrev_b32_e32 v8, 16, v203
	v_mov_b32_e32 v11, 0
	v_mov_b32_dpp v10, v10 quad_perm:[1,0,3,2] row_mask:0xf bank_mask:0xf bound_ctrl:1
	v_fmac_f32_e32 v10, v9, v9
	v_add_f32_e32 v8, v251, v8
	v_mul_f32_e32 v8, 0xbfb8aa3b, v8
	v_add_f32_dpp v10, v10, v10 quad_perm:[2,3,0,1] row_mask:0xf bank_mask:0xf bound_ctrl:1
	v_exp_f32_e32 v8, v8
	v_lshlrev_b32_e32 v7, 16, v211
	v_add_f32_dpp v10, v10, v10 row_half_mirror row_mask:0xf bank_mask:0xf bound_ctrl:1
	v_add_f32_e32 v7, v250, v7
	v_add_f32_e32 v8, 1.0, v8
	v_add_f32_dpp v10, v10, v10 row_mirror row_mask:0xf bank_mask:0xf bound_ctrl:1
	v_rcp_f32_e32 v8, v8
	v_mul_f32_e32 v7, 0xbfb8aa3b, v7
	v_mov_b32_dpp v11, v10 row_bcast:15 row_mask:0xa bank_mask:0xf
	v_add_f32_e32 v10, v10, v11
	v_mov_b32_e32 v11, 0
	v_and_b32_e32 v4, 0xffff0000, v225
	v_exp_f32_e32 v7, v7
	v_mov_b32_dpp v11, v10 row_bcast:31 row_mask:0xc bank_mask:0xf
	v_add_f32_e32 v10, v10, v11
	v_sub_f32_e32 v6, v6, v4
	v_readlane_b32 s0, v10, 63
	v_fma_f32 v6, v244, v6, v4
	v_add_f32_e32 v7, 1.0, v7
	v_max_f32_e64 v10, s0, s0
	v_max_f32_e32 v10, 0x179abe15, v10
	v_rsq_f32_e32 v10, v10
	v_rcp_f32_e32 v7, v7
	v_and_b32_e32 v0, 0xffff0000, v218
	v_sub_f32_e32 v1, v1, v0
	v_mul_f32_e32 v9, v9, v10
	v_add_f32_e32 v10, -1.0, v8
	v_fma_f32 v10, v248, v10, 1.0
	v_mul_f32_e32 v3, v10, v3
	v_mul_f32_e32 v10, v6, v3
	v_mul_f32_e32 v11, v249, v10
	v_mul_f32_e32 v7, 0xbf1b4598, v7
	v_mul_f32_e32 v7, 0x3fb8aa3b, v7
	v_mov_b32_dpp v11, v11 quad_perm:[1,0,3,2] row_mask:0xf bank_mask:0xf bound_ctrl:1
	v_fmac_f32_e32 v11, v249, v10
	v_exp_f32_e32 v7, v7
	v_fma_f32 v1, v246, v1, v0
	v_add_f32_dpp v10, v11, v11 quad_perm:[2,3,0,1] row_mask:0xf bank_mask:0xf bound_ctrl:1
	v_mov_b32_e32 v11, 0
	s_nop 0
	v_add_f32_dpp v10, v10, v10 row_half_mirror row_mask:0xf bank_mask:0xf bound_ctrl:1
	s_nop 1
	v_add_f32_dpp v10, v10, v10 row_mirror row_mask:0xf bank_mask:0xf bound_ctrl:1
	s_nop 1
	v_mov_b32_dpp v11, v10 row_bcast:15 row_mask:0xa bank_mask:0xf
	v_add_f32_e32 v10, v10, v11
	v_mov_b32_e32 v11, 0
	s_nop 1
	v_mov_b32_dpp v11, v10 row_bcast:31 row_mask:0xc bank_mask:0xf
	v_add_f32_e32 v10, v10, v11
	s_nop 0
	v_readlane_b32 s50, v10, 63
	v_add_u32_e32 v10, s52, v148
	ds_write2st64_b32 v10, v7, v9 offset1:32
	v_mul_f32_e32 v7, v8, v9
	ds_write2st64_b32 v10, v7, v3 offset0:64 offset1:96
	ds_write_b32 v10, v6 offset:32768
	v_add_u32_e32 v3, vcc_lo, v148
	ds_write_b32 v3, v1
	v_lshlrev_b32_e32 v1, 16, v195
	v_add_u32_e32 v3, vcc_hi, v148
	ds_write_b32 v3, v1
	s_and_saveexec_b64 s[72:73], s[4:5]
	s_lshl_b32 s0, s38, 2
	s_add_i32 s0, s43, s0
	v_mov_b32_e32 v1, s0
	v_mov_b32_e32 v3, s50
	ds_write_b32 v1, v3 offset:24
	s_or_b64 exec, exec, s[72:73]
	v_lshlrev_b32_e32 v7, 16, v212
	v_add_f32_e32 v7, v250, v7
	v_mul_f32_e32 v7, 0xbfb8aa3b, v7
	v_lshlrev_b32_e32 v1, 16, v176
	v_exp_f32_e32 v7, v7
	v_sub_f32_e32 v4, v4, v1
	v_lshlrev_b32_e32 v3, 16, v214
	v_fmac_f32_e32 v1, v244, v4
	v_lshlrev_b32_e32 v4, 16, v204
	v_sub_f32_e32 v2, v2, v3
	v_add_f32_e32 v4, v251, v4
	v_fmac_f32_e32 v3, v245, v2
	v_add_f32_e32 v2, 1.0, v7
	v_mul_f32_e32 v4, 0xbfb8aa3b, v4
	v_rcp_f32_e32 v2, v2
	v_exp_f32_e32 v4, v4
	v_lshlrev_b32_e32 v6, 16, v219
	v_sub_f32_e32 v0, v0, v6
	v_fmac_f32_e32 v6, v246, v0
	v_mul_f32_e32 v0, 0xbf1b4598, v2
	v_add_f32_e32 v2, 1.0, v4
	v_mul_f32_e32 v4, v247, v3
	v_mul_f32_e32 v7, v4, v4
	v_mov_b32_e32 v8, 0
	v_rcp_f32_e32 v2, v2
	v_mov_b32_dpp v7, v7 quad_perm:[1,0,3,2] row_mask:0xf bank_mask:0xf bound_ctrl:1
	v_fmac_f32_e32 v7, v4, v4
	v_mul_f32_e32 v0, 0x3fb8aa3b, v0
	v_exp_f32_e32 v0, v0
	v_add_f32_dpp v7, v7, v7 quad_perm:[2,3,0,1] row_mask:0xf bank_mask:0xf bound_ctrl:1
	s_nop 1
	v_add_f32_dpp v7, v7, v7 row_half_mirror row_mask:0xf bank_mask:0xf bound_ctrl:1
	s_nop 1
	v_add_f32_dpp v7, v7, v7 row_mirror row_mask:0xf bank_mask:0xf bound_ctrl:1
	s_nop 1
	v_mov_b32_dpp v8, v7 row_bcast:15 row_mask:0xa bank_mask:0xf
	v_add_f32_e32 v7, v7, v8
	v_mov_b32_e32 v8, 0
	s_nop 1
	v_mov_b32_dpp v8, v7 row_bcast:31 row_mask:0xc bank_mask:0xf
	v_add_f32_e32 v7, v7, v8
	s_nop 0
	v_readlane_b32 s0, v7, 63
	s_nop 1
	v_max_f32_e64 v7, s0, s0
	v_max_f32_e32 v7, 0x179abe15, v7
	v_rsq_f32_e32 v7, v7
	s_nop 0
	v_mul_f32_e32 v4, v4, v7
	v_add_f32_e32 v7, -1.0, v2
	v_fma_f32 v7, v248, v7, 1.0
	v_mul_f32_e32 v3, v7, v3
	v_mul_f32_e32 v7, v1, v3
	v_mul_f32_e32 v8, v249, v7
	s_nop 1
	v_mov_b32_dpp v8, v8 quad_perm:[1,0,3,2] row_mask:0xf bank_mask:0xf bound_ctrl:1
	v_fmac_f32_e32 v8, v249, v7
	s_nop 1
	v_add_f32_dpp v7, v8, v8 quad_perm:[2,3,0,1] row_mask:0xf bank_mask:0xf bound_ctrl:1
	v_mov_b32_e32 v8, 0
	s_nop 0
	v_add_f32_dpp v7, v7, v7 row_half_mirror row_mask:0xf bank_mask:0xf bound_ctrl:1
	s_nop 1
	v_add_f32_dpp v7, v7, v7 row_mirror row_mask:0xf bank_mask:0xf bound_ctrl:1
	s_nop 1
	v_mov_b32_dpp v8, v7 row_bcast:15 row_mask:0xa bank_mask:0xf
	v_add_f32_e32 v7, v7, v8
	v_mov_b32_e32 v8, 0
	s_nop 1
	v_mov_b32_dpp v8, v7 row_bcast:31 row_mask:0xc bank_mask:0xf
	v_add_f32_e32 v7, v7, v8
	s_nop 0
	v_readlane_b32 s50, v7, 63
	v_add_u32_e32 v7, s52, v152
	ds_write2st64_b32 v7, v0, v4 offset1:32
	v_mul_f32_e32 v0, v2, v4
	ds_write2st64_b32 v7, v0, v3 offset0:64 offset1:96
	ds_write_b32 v7, v1 offset:32768
	v_add_u32_e32 v0, vcc_lo, v152
	ds_write_b32 v0, v6
	v_lshlrev_b32_e32 v0, 16, v196
	v_add_u32_e32 v1, vcc_hi, v152
	ds_write_b32 v1, v0
	s_and_saveexec_b64 s[72:73], s[4:5]
	s_lshl_b32 s0, s38, 2
	s_add_i32 s0, s43, s0
	v_mov_b32_e32 v0, s0
	v_mov_b32_e32 v1, s50
	ds_write_b32 v0, v1 offset:28
	s_or_b64 exec, exec, s[72:73]
	s_cmp_gt_u32 s42, 61
	s_cbranch_scc1 .LBB0_2525
	s_lshl_b32 s0, s42, 5
	s_add_i32 s72, s0, s40
	s_add_i32 s52, s72, -1
	s_lshl_b64 s[0:1], s[52:53], 12
	s_mov_b32 s73, s53
	v_lshl_add_u64 v[0:1], v[86:87], 0, s[0:1]
	s_lshl_b64 s[0:1], s[72:73], 12
	global_load_ushort v40, v[0:1], off
	global_load_ushort v60, v[0:1], off offset:1024
	global_load_ushort v61, v[0:1], off offset:2048
	v_lshl_add_u64 v[0:1], v[86:87], 0, s[0:1]
	s_lshl_b32 s52, s72, 12
	global_load_ushort v41, v[0:1], off
	global_load_ushort v42, v[0:1], off offset:1024
	global_load_ushort v62, v[0:1], off offset:2048
	v_lshl_add_u64 v[0:1], v[86:87], 0, s[52:53]
	v_add_co_u32_e32 v2, vcc, s66, v0
	s_movk_i32 s51, 0x3000
	s_nop 0
	v_addc_co_u32_e32 v3, vcc, 0, v1, vcc
	v_add_co_u32_e32 v6, vcc, s67, v0
	s_movk_i32 s50, 0x4000
	s_nop 0
	v_addc_co_u32_e32 v7, vcc, 0, v1, vcc
	global_load_ushort v43, v[6:7], off offset:-4096
	global_load_ushort v44, v[2:3], off offset:1024
	global_load_ushort v63, v[2:3], off offset:2048
	global_load_ushort v45, v[6:7], off
	global_load_ushort v46, v[6:7], off offset:1024
	global_load_ushort v64, v[6:7], off offset:2048
	v_add_co_u32_e32 v2, vcc, s51, v0
	s_movk_i32 s52, 0x5000
	s_nop 0
	v_addc_co_u32_e32 v3, vcc, 0, v1, vcc
	v_add_co_u32_e32 v6, vcc, s50, v0
	s_movk_i32 s0, 0x6000
	s_nop 0
	v_addc_co_u32_e32 v7, vcc, 0, v1, vcc
	global_load_ushort v47, v[6:7], off offset:-4096
	global_load_ushort v48, v[2:3], off offset:1024
	global_load_ushort v49, v[2:3], off offset:2048
	global_load_ushort v50, v[6:7], off
	global_load_ushort v51, v[6:7], off offset:1024
	global_load_ushort v52, v[6:7], off offset:2048
	v_add_co_u32_e32 v2, vcc, s52, v0
	s_movk_i32 s68, 0x5000
	s_nop 0
	v_addc_co_u32_e32 v3, vcc, 0, v1, vcc
	v_add_co_u32_e32 v6, vcc, s0, v0
	s_movk_i32 s0, 0x7000
	s_nop 0
	v_addc_co_u32_e32 v7, vcc, 0, v1, vcc
	global_load_ushort v53, v[6:7], off offset:-4096
	global_load_ushort v54, v[2:3], off offset:1024
	global_load_ushort v55, v[2:3], off offset:2048
	global_load_ushort v56, v[6:7], off
	global_load_ushort v57, v[6:7], off offset:1024
	global_load_ushort v58, v[6:7], off offset:2048
	v_add_co_u32_e32 v2, vcc, s0, v0
	s_add_u32 s0, s84, s72
	s_addc_u32 s1, s85, 0
	v_addc_co_u32_e32 v3, vcc, 0, v1, vcc
	s_mul_i32 s43, s1, 0xc00
	v_mad_u64_u32 v[16:17], s[0:1], s0, v236, v[88:89]
	v_add_u32_e32 v17, s43, v17
	v_add_co_u32_e32 v10, vcc, s66, v16
	global_load_ushort v176, v[2:3], off
	global_load_ushort v214, v[2:3], off offset:1024
	s_nop 0
	global_load_ushort v219, v[2:3], off offset:2048
	v_addc_co_u32_e32 v11, vcc, 0, v17, vcc
	v_add_co_u32_e32 v18, vcc, s67, v16
	global_load_ushort v205, v[16:17], off
	global_load_ushort v197, v[16:17], off offset:1024
	global_load_ushort v177, v[16:17], off offset:2048
	global_load_ushort v206, v[16:17], off offset:3072
	v_addc_co_u32_e32 v19, vcc, 0, v17, vcc
	global_load_ushort v198, v[18:19], off offset:-4096
	global_load_ushort v190, v[10:11], off offset:1024
	global_load_ushort v207, v[10:11], off offset:2048
	global_load_ushort v199, v[10:11], off offset:3072
	s_nop 0
	global_load_ushort v191, v[18:19], off
	global_load_ushort v208, v[18:19], off offset:1024
	global_load_ushort v200, v[18:19], off offset:2048
	global_load_ushort v192, v[18:19], off offset:3072
	v_add_co_u32_e32 v18, vcc, s51, v16
	v_addc_co_u32_e32 v19, vcc, 0, v17, vcc
	v_add_co_u32_e32 v22, vcc, s50, v16
	s_nop 0
	v_addc_co_u32_e32 v23, vcc, 0, v17, vcc
	global_load_ushort v209, v[22:23], off offset:-4096
	global_load_ushort v201, v[18:19], off offset:1024
	global_load_ushort v193, v[18:19], off offset:2048
	global_load_ushort v210, v[18:19], off offset:3072
	global_load_ushort v202, v[22:23], off
	global_load_ushort v194, v[22:23], off offset:1024
	global_load_ushort v211, v[22:23], off offset:2048
	global_load_ushort v203, v[22:23], off offset:3072
	v_add_co_u32_e32 v16, vcc, s52, v16
	v_addc_co_u32_e32 v17, vcc, 0, v17, vcc
	global_load_ushort v195, v[16:17], off
	global_load_ushort v212, v[16:17], off offset:1024
	global_load_ushort v204, v[16:17], off offset:2048
	global_load_ushort v196, v[16:17], off offset:3072

; __device__ __forceinline__ float shfl_xor_l(float v, int m, int lane) { return __int_as_float(__builtin_amdgcn_ds_bpermute((lane ^ m) << 2, __float_as_int(v))); }
; __device__ __forceinline__ unsigned cvt_pk_bf16(float lo, float hi) { unsigned r; asm volatile("s_nop 0\n\tv_cvt_pk_bf16_f32 %0, %1, %2" : "=v"(r) : "v"(lo), "v"(hi)); return r; }
; __device__ __forceinline__ void phase_attn(KP P, int l_, unsigned char* shm) {
;     ...
;                     float mloc = st[0][0];
; #pragma unroll
;                     for (int kt = 0; kt < 4; ++kt)
; #pragma unroll
;                         for (int jj = 0; jj < 4; ++jj) mloc = fmaxf(mloc, st[kt][jj]);
;                     mloc = fmaxf(mloc, shfl_xor_l(mloc, 16, lane)); mloc = fmaxf(mloc, shfl_xor_l(mloc, 32, lane));
;                     const float mnew = fmaxf(mrun, mloc), alpha = __builtin_amdgcn_exp2f(mrun - mnew);
;                     mrun = mnew;
;                     float psum = 0.f;
; #pragma unroll
;                     for (int kt = 0; kt < 4; ++kt)
; #pragma unroll
;                         for (int jj = 0; jj < 4; ++jj) { const float p = __builtin_amdgcn_exp2f(st[kt][jj] - mnew); st[kt][jj] = p; psum += p; }
;                     lrun = lrun * alpha + psum;
; #pragma unroll
;                     for (int e = 0; e < 8; ++e) ot[e] *= alpha;
;                     bf16x8 pb[2];
; #pragma unroll
;                     for (int k2 = 0; k2 < 2; ++k2) { uint4 pk; pk.x = cvt_pk_bf16(st[2 * k2][0], st[2 * k2][1]); pk.y = cvt_pk_bf16(st[2 * k2][2], st[2 * k2][3]);
;                         pk.z = cvt_pk_bf16(st[2 * k2 + 1][0], st[2 * k2 + 1][1]); pk.w = cvt_pk_bf16(st[2 * k2 + 1][2], st[2 * k2 + 1][3]);
;                         pb[k2] = as_bf16x8(pk); }
; #pragma unroll
;                     for (int e = 0; e < 8; ++e)
; #pragma unroll
;                         for (int k2 = 0; k2 < 2; ++k2) { const uint2 v0 = vfa[e][k2], v1 = vfb[e][k2];
;                             uint4 vv; vv.x = v0.x; vv.y = v0.y; vv.z = v1.x; vv.w = v1.y;
;                             ot[e] = __builtin_amdgcn_mfma_f32_16x16x32_bf16(as_bf16x8(vv), pb[k2], ot[e], 0, 0, 0); }
.LBB0_2658:
	s_nop 0
	v_max_f32_e32 v186, v151, v151
	v_max_f32_e32 v187, v150, v150
	v_max_f32_e32 v186, v187, v186
	v_max3_f32 v186, v186, v152, v153
	v_max3_f32 v186, v186, v146, v147
	v_max3_f32 v186, v186, v148, v149
	v_max3_f32 v186, v186, v138, v139
	v_max3_f32 v186, v186, v140, v141
	v_max3_f32 v186, v186, v142, v143
	v_max3_f32 v186, v186, v144, v145
	v_mov_b32_e32 v187, v186
	s_nop 1
	v_permlane16_swap_b32_e32 v187, v186
	v_max_f32_e32 v186, v186, v187
	v_mov_b32_e32 v187, v186
	s_nop 1
	v_permlane32_swap_b32_e32 v187, v186
	v_max3_f32 v211, v210, v186, v187
	v_sub_f32_e32 v150, v150, v211
	v_exp_f32_e32 v150, v150
	v_sub_f32_e32 v151, v151, v211
	v_exp_f32_e32 v151, v151
	v_sub_f32_e32 v152, v152, v211
	v_exp_f32_e32 v152, v152
	v_sub_f32_e32 v153, v153, v211
	v_exp_f32_e32 v153, v153
	v_sub_f32_e32 v146, v146, v211
	v_add_f32_e32 v187, 0, v150
	v_exp_f32_e32 v146, v146
	v_sub_f32_e32 v147, v147, v211
	v_add_f32_e32 v187, v151, v187
	v_exp_f32_e32 v147, v147
	v_sub_f32_e32 v148, v148, v211
	v_add_f32_e32 v187, v152, v187
	v_exp_f32_e32 v148, v148
	v_sub_f32_e32 v149, v149, v211
	v_add_f32_e32 v187, v153, v187
	v_exp_f32_e32 v149, v149
	v_sub_f32_e32 v138, v138, v211
	v_sub_f32_e32 v186, v210, v211
	v_add_f32_e32 v187, v146, v187
	v_exp_f32_e32 v210, v138
	v_add_f32_e32 v187, v147, v187
	v_add_f32_e32 v187, v148, v187
	v_sub_f32_e32 v139, v139, v211
	v_add_f32_e32 v187, v149, v187
	v_exp_f32_e32 v139, v139
	v_sub_f32_e32 v140, v140, v211
	v_add_f32_e32 v138, v210, v187
	v_exp_f32_e32 v187, v140
	v_sub_f32_e32 v140, v141, v211
	v_exp_f32_e32 v212, v140
	v_add_f32_e32 v138, v139, v138
	v_add_f32_e32 v138, v187, v138
	v_add_f32_e32 v140, v212, v138
	v_sub_f32_e32 v138, v142, v211
	v_exp_f32_e32 v213, v138
	v_sub_f32_e32 v138, v143, v211
	v_exp_f32_e32 v214, v138
	v_sub_f32_e32 v138, v144, v211
	v_exp_f32_e32 v215, v138
	v_sub_f32_e32 v138, v145, v211
	v_exp_f32_e32 v216, v138
	v_exp_f32_e32 v138, v186
	v_add_f32_e32 v140, v213, v140
	v_add_f32_e32 v140, v214, v140
	v_add_f32_e32 v140, v215, v140
	v_pk_mul_f32 v[60:61], v[60:61], v[138:139] op_sel_hi:[1,0]
	v_pk_mul_f32 v[58:59], v[58:59], v[138:139] op_sel_hi:[1,0]
	v_pk_mul_f32 v[52:53], v[52:53], v[138:139] op_sel_hi:[1,0]
	v_pk_mul_f32 v[50:51], v[50:51], v[138:139] op_sel_hi:[1,0]
	v_pk_mul_f32 v[44:45], v[44:45], v[138:139] op_sel_hi:[1,0]
	v_pk_mul_f32 v[42:43], v[42:43], v[138:139] op_sel_hi:[1,0]
	v_pk_mul_f32 v[48:49], v[48:49], v[138:139] op_sel_hi:[1,0]
	v_pk_mul_f32 v[46:47], v[46:47], v[138:139] op_sel_hi:[1,0]
	v_pk_mul_f32 v[56:57], v[56:57], v[138:139] op_sel_hi:[1,0]
	v_pk_mul_f32 v[54:55], v[54:55], v[138:139] op_sel_hi:[1,0]
	v_pk_mul_f32 v[64:65], v[64:65], v[138:139] op_sel_hi:[1,0]
	v_pk_mul_f32 v[62:63], v[62:63], v[138:139] op_sel_hi:[1,0]
	v_pk_mul_f32 v[68:69], v[68:69], v[138:139] op_sel_hi:[1,0]
	v_pk_mul_f32 v[66:67], v[66:67], v[138:139] op_sel_hi:[1,0]
	v_pk_mul_f32 v[72:73], v[72:73], v[138:139] op_sel_hi:[1,0]
	v_pk_mul_f32 v[70:71], v[70:71], v[138:139] op_sel_hi:[1,0]
	v_add_f32_e32 v186, v216, v140
	s_nop 0
	v_cvt_pk_bf16_f32 v140, v150, v151
	s_nop 0
	v_cvt_pk_bf16_f32 v141, v152, v153
	s_nop 0
	v_cvt_pk_bf16_f32 v142, v146, v147
	s_nop 0
	v_cvt_pk_bf16_f32 v143, v148, v149
	s_nop 0
	v_cvt_pk_bf16_f32 v144, v210, v139
	s_nop 0
	v_cvt_pk_bf16_f32 v145, v187, v212
	s_nop 0
	v_cvt_pk_bf16_f32 v146, v213, v214
	s_nop 0
	v_cvt_pk_bf16_f32 v147, v215, v216
	v_fmac_f32_e32 v186, v171, v138
	s_waitcnt lgkmcnt(0)
	v_mfma_f32_16x16x32_bf16 v[58:61], v[134:137], v[140:143], v[58:61]
	v_mov_b32_e32 v210, v211
	v_mov_b32_e32 v171, v186
	v_mfma_f32_16x16x32_bf16 v[50:53], v[126:129], v[140:143], v[50:53]
	v_mfma_f32_16x16x32_bf16 v[42:45], v[118:121], v[140:143], v[42:45]
	v_mfma_f32_16x16x32_bf16 v[46:49], v[110:113], v[140:143], v[46:49]
	v_mfma_f32_16x16x32_bf16 v[54:57], v[102:105], v[140:143], v[54:57]
	v_mfma_f32_16x16x32_bf16 v[62:65], v[94:97], v[140:143], v[62:65]
	v_mfma_f32_16x16x32_bf16 v[66:69], v[86:89], v[140:143], v[66:69]
	v_mfma_f32_16x16x32_bf16 v[70:73], v[78:81], v[140:143], v[70:73]
	v_mfma_f32_16x16x32_bf16 v[58:61], v[130:133], v[144:147], v[58:61]
	v_mfma_f32_16x16x32_bf16 v[50:53], v[122:125], v[144:147], v[50:53]
	v_mfma_f32_16x16x32_bf16 v[42:45], v[114:117], v[144:147], v[42:45]
	v_mfma_f32_16x16x32_bf16 v[46:49], v[106:109], v[144:147], v[46:49]
	v_mfma_f32_16x16x32_bf16 v[54:57], v[98:101], v[144:147], v[54:57]
	v_mfma_f32_16x16x32_bf16 v[62:65], v[90:93], v[144:147], v[62:65]
	v_mfma_f32_16x16x32_bf16 v[66:69], v[82:85], v[144:147], v[66:69]
	v_mfma_f32_16x16x32_bf16 v[70:73], v[74:77], v[144:147], v[70:73]
	s_cmp_ge_u32 s52, s58
	s_cbranch_scc1 .LBB0_2655

; __device__ __forceinline__ float shfl_xor_l(float v, int m, int lane) { return __int_as_float(__builtin_amdgcn_ds_bpermute((lane ^ m) << 2, __float_as_int(v))); }
; __device__ __forceinline__ unsigned cvt_pk_bf16(float lo, float hi) { unsigned r; asm volatile("s_nop 0\n\tv_cvt_pk_bf16_f32 %0, %1, %2" : "=v"(r) : "v"(lo), "v"(hi)); return r; }
; __device__ __forceinline__ void phase_attn(KP P, int l_, unsigned char* shm) {
;     ...
;                     float mloc = st[0][0];
; #pragma unroll
;                     for (int kt = 0; kt < 4; ++kt)
; #pragma unroll
;                         for (int jj = 0; jj < 4; ++jj) mloc = fmaxf(mloc, st[kt][jj]);
;                     mloc = fmaxf(mloc, shfl_xor_l(mloc, 16, lane)); mloc = fmaxf(mloc, shfl_xor_l(mloc, 32, lane));
;                     const float mnew = fmaxf(mrun, mloc), alpha = __builtin_amdgcn_exp2f(mrun - mnew);
;                     mrun = mnew;
;                     float psum = 0.f;
; #pragma unroll
;                     for (int kt = 0; kt < 4; ++kt)
; #pragma unroll
;                         for (int jj = 0; jj < 4; ++jj) { const float p = __builtin_amdgcn_exp2f(st[kt][jj] - mnew); st[kt][jj] = p; psum += p; }
;                     lrun = lrun * alpha + psum;
; #pragma unroll
;                     for (int e = 0; e < 8; ++e) ot[e] *= alpha;
;                     bf16x8 pb[2];
; #pragma unroll
;                     for (int k2 = 0; k2 < 2; ++k2) { uint4 pk; pk.x = cvt_pk_bf16(st[2 * k2][0], st[2 * k2][1]); pk.y = cvt_pk_bf16(st[2 * k2][2], st[2 * k2][3]);
;                         pk.z = cvt_pk_bf16(st[2 * k2 + 1][0], st[2 * k2 + 1][1]); pk.w = cvt_pk_bf16(st[2 * k2 + 1][2], st[2 * k2 + 1][3]);
;                         pb[k2] = as_bf16x8(pk); }
; #pragma unroll
;                     for (int e = 0; e < 8; ++e)
; #pragma unroll
;                         for (int k2 = 0; k2 < 2; ++k2) { const uint2 v0 = vfa[e][k2], v1 = vfb[e][k2];
;                             uint4 vv; vv.x = v0.x; vv.y = v0.y; vv.z = v1.x; vv.w = v1.y;
;                             ot[e] = __builtin_amdgcn_mfma_f32_16x16x32_bf16(as_bf16x8(vv), pb[k2], ot[e], 0, 0, 0); }
;                 }
;             }
;             if (t + 1 < nt) ATT_LSTORE((t + 1) & 1);
;             __syncthreads();
.LBB0_2661:
	s_nop 0
	v_max_f32_e32 v173, v151, v151
	v_max_f32_e32 v186, v150, v150
	v_max_f32_e32 v173, v186, v173
	v_max3_f32 v173, v173, v152, v153
	v_max3_f32 v173, v173, v146, v147
	v_max3_f32 v173, v173, v148, v149
	v_max3_f32 v173, v173, v138, v139
	v_max3_f32 v173, v173, v140, v141
	v_max3_f32 v173, v173, v142, v143
	v_max3_f32 v173, v173, v144, v145
	v_mov_b32_e32 v186, v173
	s_nop 1
	v_permlane16_swap_b32_e32 v186, v173
	v_max_f32_e32 v173, v173, v186
	v_mov_b32_e32 v186, v173
	s_nop 1
	v_permlane32_swap_b32_e32 v186, v173
	v_max3_f32 v173, v210, v173, v186
	v_sub_f32_e32 v150, v150, v173
	v_exp_f32_e32 v150, v150
	v_sub_f32_e32 v151, v151, v173
	v_exp_f32_e32 v151, v151
	v_sub_f32_e32 v152, v152, v173
	v_exp_f32_e32 v152, v152
	v_sub_f32_e32 v153, v153, v173
	v_exp_f32_e32 v153, v153
	v_sub_f32_e32 v146, v146, v173
	v_add_f32_e32 v187, 0, v150
	v_exp_f32_e32 v146, v146
	v_sub_f32_e32 v147, v147, v173
	v_add_f32_e32 v187, v151, v187
	v_exp_f32_e32 v147, v147
	v_sub_f32_e32 v148, v148, v173
	v_add_f32_e32 v187, v152, v187
	v_exp_f32_e32 v148, v148
	v_sub_f32_e32 v149, v149, v173
	v_add_f32_e32 v187, v153, v187
	v_exp_f32_e32 v149, v149
	v_sub_f32_e32 v138, v138, v173
	v_add_f32_e32 v187, v146, v187
	v_exp_f32_e32 v202, v138
	v_add_f32_e32 v187, v147, v187
	v_add_f32_e32 v187, v148, v187
	v_sub_f32_e32 v139, v139, v173
	v_add_f32_e32 v187, v149, v187
	v_exp_f32_e32 v139, v139
	v_sub_f32_e32 v140, v140, v173
	v_add_f32_e32 v138, v202, v187
	v_exp_f32_e32 v187, v140
	v_sub_f32_e32 v140, v141, v173
	v_exp_f32_e32 v203, v140
	v_add_f32_e32 v138, v139, v138
	v_add_f32_e32 v138, v187, v138
	v_sub_f32_e32 v186, v210, v173
	v_add_f32_e32 v140, v203, v138
	v_sub_f32_e32 v138, v142, v173
	v_exp_f32_e32 v204, v138
	v_sub_f32_e32 v138, v143, v173
	v_exp_f32_e32 v205, v138
	v_sub_f32_e32 v138, v144, v173
	v_exp_f32_e32 v206, v138
	v_sub_f32_e32 v138, v145, v173
	v_exp_f32_e32 v207, v138
	v_exp_f32_e32 v138, v186
	v_add_f32_e32 v140, v204, v140
	v_add_f32_e32 v140, v205, v140
	v_add_f32_e32 v140, v206, v140
	v_pk_mul_f32 v[60:61], v[60:61], v[138:139] op_sel_hi:[1,0]
	v_pk_mul_f32 v[58:59], v[58:59], v[138:139] op_sel_hi:[1,0]
	v_pk_mul_f32 v[52:53], v[52:53], v[138:139] op_sel_hi:[1,0]
	v_pk_mul_f32 v[50:51], v[50:51], v[138:139] op_sel_hi:[1,0]
	v_pk_mul_f32 v[44:45], v[44:45], v[138:139] op_sel_hi:[1,0]
	v_pk_mul_f32 v[42:43], v[42:43], v[138:139] op_sel_hi:[1,0]
	v_pk_mul_f32 v[48:49], v[48:49], v[138:139] op_sel_hi:[1,0]
	v_pk_mul_f32 v[46:47], v[46:47], v[138:139] op_sel_hi:[1,0]
	v_pk_mul_f32 v[56:57], v[56:57], v[138:139] op_sel_hi:[1,0]
	v_pk_mul_f32 v[54:55], v[54:55], v[138:139] op_sel_hi:[1,0]
	v_pk_mul_f32 v[64:65], v[64:65], v[138:139] op_sel_hi:[1,0]
	v_pk_mul_f32 v[62:63], v[62:63], v[138:139] op_sel_hi:[1,0]
	v_pk_mul_f32 v[68:69], v[68:69], v[138:139] op_sel_hi:[1,0]
	v_pk_mul_f32 v[66:67], v[66:67], v[138:139] op_sel_hi:[1,0]
	v_pk_mul_f32 v[72:73], v[72:73], v[138:139] op_sel_hi:[1,0]
	v_pk_mul_f32 v[70:71], v[70:71], v[138:139] op_sel_hi:[1,0]
	v_add_f32_e32 v186, v207, v140
	s_nop 0
	v_cvt_pk_bf16_f32 v140, v150, v151
	s_nop 0
	v_cvt_pk_bf16_f32 v141, v152, v153
	s_nop 0
	v_cvt_pk_bf16_f32 v142, v146, v147
	s_nop 0
	v_cvt_pk_bf16_f32 v143, v148, v149
	s_nop 0
	v_cvt_pk_bf16_f32 v144, v202, v139
	s_nop 0
	v_cvt_pk_bf16_f32 v145, v187, v203
	s_nop 0
	v_cvt_pk_bf16_f32 v146, v204, v205
	s_nop 0
	v_cvt_pk_bf16_f32 v147, v206, v207
	v_fmac_f32_e32 v186, v171, v138
	s_waitcnt lgkmcnt(0)
	v_mfma_f32_16x16x32_bf16 v[58:61], v[134:137], v[140:143], v[58:61]
	v_mov_b32_e32 v210, v173
	v_mov_b32_e32 v171, v186
	v_mfma_f32_16x16x32_bf16 v[50:53], v[126:129], v[140:143], v[50:53]
	v_mfma_f32_16x16x32_bf16 v[42:45], v[118:121], v[140:143], v[42:45]
	v_mfma_f32_16x16x32_bf16 v[46:49], v[110:113], v[140:143], v[46:49]
	v_mfma_f32_16x16x32_bf16 v[54:57], v[102:105], v[140:143], v[54:57]
	v_mfma_f32_16x16x32_bf16 v[62:65], v[94:97], v[140:143], v[62:65]
	v_mfma_f32_16x16x32_bf16 v[66:69], v[86:89], v[140:143], v[66:69]
	v_mfma_f32_16x16x32_bf16 v[70:73], v[78:81], v[140:143], v[70:73]
	v_mfma_f32_16x16x32_bf16 v[58:61], v[130:133], v[144:147], v[58:61]
	v_mfma_f32_16x16x32_bf16 v[50:53], v[122:125], v[144:147], v[50:53]
	v_mfma_f32_16x16x32_bf16 v[42:45], v[114:117], v[144:147], v[42:45]
	v_mfma_f32_16x16x32_bf16 v[46:49], v[106:109], v[144:147], v[46:49]
	v_mfma_f32_16x16x32_bf16 v[54:57], v[98:101], v[144:147], v[54:57]
	v_mfma_f32_16x16x32_bf16 v[62:65], v[90:93], v[144:147], v[62:65]
	v_mfma_f32_16x16x32_bf16 v[66:69], v[82:85], v[144:147], v[66:69]
	v_mfma_f32_16x16x32_bf16 v[70:73], v[74:77], v[144:147], v[70:73]
	s_andn2_b64 vcc, exec, s[56:57]
	s_add_i32 s70, s70, 1
	s_cbranch_vccnz .LBB0_2650
